# layer-1 convpool: conv half's address set-up + loads issued before the pool half's arithmetic (loads of both lane halves in flight together)
# baseline (speedup 1.0000x reference)
.LBB0_399:
	v_readlane_b32 s24, v255, 1
	v_readlane_b32 s25, v255, 2
	s_andn2_b64 vcc, exec, s[24:25]
	s_mov_b64 s[24:25], -1
	s_cbranch_vccnz .LBB0_405
	v_readlane_b32 s0, v252, 56
	v_readlane_b32 s24, v254, 58
	s_add_i32 s0, s24, s0
	v_mov_b32_e32 v1, v244
	s_lshl_b32 s39, s0, 3
	v_readlane_b32 s25, v254, 59
	v_cmp_lt_i32_e32 vcc, 31, v1
	v_med3_i32 v0, s39, 0, v243
	s_and_saveexec_b64 s[24:25], vcc
	s_xor_b64 s[24:25], exec, s[24:25]
	s_cbranch_execz .LBB0_402
	v_subrev_u32_e32 v1, 32, v1
	s_add_i32 s42, s39, -8
	v_lshlrev_b32_e32 v32, 3, v1
	v_lshrrev_b32_e32 v37, 3, v1
	v_med3_i32 v1, s42, 0, v243
	v_readlane_b32 s51, v253, 4
	s_add_i32 s50, s39, -7
	s_add_i32 s49, s39, -6
	v_or_b32_e32 v1, s51, v1
	v_lshlrev_b32_e32 v2, 11, v1
	v_med3_i32 v1, s50, 0, v243
	v_or_b32_e32 v1, s51, v1
	v_readlane_b32 s52, v252, 5
	v_lshlrev_b64 v[34:35], 1, v[32:33]
	v_lshlrev_b32_e32 v32, 11, v1
	v_med3_i32 v1, s49, 0, v243
	v_mov_b32_e32 v3, v33
	v_readlane_b32 s53, v252, 6
	v_or_b32_e32 v1, s51, v1
	s_add_i32 s48, s39, -5
	v_lshl_add_u64 v[2:3], s[52:53], 0, v[2:3]
	v_lshl_add_u64 v[4:5], s[52:53], 0, v[32:33]
	v_lshlrev_b32_e32 v32, 11, v1
	v_med3_i32 v1, s48, 0, v243
	v_lshl_add_u64 v[2:3], v[2:3], 0, v[34:35]
	v_or_b32_e32 v1, s51, v1
	s_add_i32 s31, s39, -4
	v_lshl_add_u64 v[4:5], v[4:5], 0, v[34:35]
	global_load_dwordx4 v[66:69], v[2:3], off offset:1536
	global_load_dwordx4 v[62:65], v[4:5], off offset:1536
	v_lshl_add_u64 v[2:3], s[52:53], 0, v[32:33]
	v_lshlrev_b32_e32 v32, 11, v1
	v_med3_i32 v1, s31, 0, v243
	v_or_b32_e32 v1, s51, v1
	s_add_i32 s30, s39, -3
	v_lshl_add_u64 v[4:5], s[52:53], 0, v[32:33]
	v_lshlrev_b32_e32 v32, 11, v1
	v_med3_i32 v1, s30, 0, v243
	s_max_i32 s26, s39, 1
	v_lshl_add_u64 v[2:3], v[2:3], 0, v[34:35]
	v_or_b32_e32 v1, s51, v1
	s_add_i32 s47, s39, -2
	s_add_i32 s26, s26, -1
	v_lshl_add_u64 v[4:5], v[4:5], 0, v[34:35]
	global_load_dwordx4 v[82:85], v[2:3], off offset:1536
	global_load_dwordx4 v[70:73], v[4:5], off offset:1536
	v_lshl_add_u64 v[2:3], s[52:53], 0, v[32:33]
	v_lshlrev_b32_e32 v32, 11, v1
	v_med3_i32 v1, s47, 0, v243
	s_min_u32 s26, s26, 0x7ff
	v_or_b32_e32 v1, s51, v1
	s_or_b32 s26, s26, s51
	v_lshl_add_u64 v[2:3], v[2:3], 0, v[34:35]
	v_lshl_add_u64 v[4:5], s[52:53], 0, v[32:33]
	v_lshlrev_b32_e32 v32, 11, v1
	s_lshl_b32 s26, s26, 11
	v_lshl_add_u64 v[4:5], v[4:5], 0, v[34:35]
	global_load_dwordx4 v[90:93], v[2:3], off offset:1536
	global_load_dwordx4 v[86:89], v[4:5], off offset:1536
	v_lshl_add_u64 v[2:3], s[52:53], 0, v[32:33]
	s_add_u32 s26, s52, s26
	v_lshl_add_u64 v[2:3], v[2:3], 0, v[34:35]
	s_addc_u32 s27, s53, 0
	v_lshl_add_u64 v[4:5], s[26:27], 0, v[34:35]
	global_load_dwordx4 v[94:97], v[2:3], off offset:1536
	global_load_dwordx4 v[78:81], v[4:5], off offset:1536
	s_or_b32 s34, s39, 1
	v_or_b32_e32 v0, s51, v0
	v_med3_i32 v2, s34, 0, v243
	v_lshlrev_b32_e32 v32, 11, v0
	v_or_b32_e32 v2, s51, v2
	v_lshl_add_u64 v[0:1], s[52:53], 0, v[32:33]
	v_lshlrev_b32_e32 v32, 11, v2
	v_lshl_add_u64 v[0:1], v[0:1], 0, v[34:35]
	v_lshl_add_u64 v[2:3], s[52:53], 0, v[32:33]
	s_or_b32 s35, s39, 2
	v_lshl_add_u64 v[2:3], v[2:3], 0, v[34:35]
	global_load_dwordx4 v[28:31], v[0:1], off offset:1536
	global_load_dwordx4 v[74:77], v[2:3], off offset:1536
	v_med3_i32 v0, s35, 0, v243
	s_or_b32 s40, s39, 3
	v_or_b32_e32 v0, s51, v0
	v_med3_i32 v2, s40, 0, v243
	v_lshlrev_b32_e32 v32, 11, v0
	v_or_b32_e32 v2, s51, v2
	v_lshl_add_u64 v[0:1], s[52:53], 0, v[32:33]
	v_lshlrev_b32_e32 v32, 11, v2
	v_lshl_add_u64 v[0:1], v[0:1], 0, v[34:35]
	v_lshl_add_u64 v[2:3], s[52:53], 0, v[32:33]
	s_or_b32 s41, s39, 4
	s_max_i32 s43, s39, -8
	v_lshl_add_u64 v[2:3], v[2:3], 0, v[34:35]
	global_load_dwordx4 v[42:45], v[0:1], off offset:1536
	global_load_dwordx4 v[38:41], v[2:3], off offset:1536
	v_med3_i32 v0, s41, 0, v243
	s_or_b32 s46, s39, 5
	s_add_i32 s43, s43, 8
	v_or_b32_e32 v0, s51, v0
	v_med3_i32 v2, s46, 0, v243
	s_min_u32 s43, s43, 0x7ff
	v_lshlrev_b32_e32 v32, 11, v0
	v_or_b32_e32 v2, s51, v2
	s_or_b32 s43, s43, s51
	v_lshl_add_u64 v[0:1], s[52:53], 0, v[32:33]
	v_lshlrev_b32_e32 v32, 11, v2
	s_or_b32 s26, s39, 6
	s_or_b32 s27, s39, 7
	s_lshl_b32 s43, s43, 11
	v_lshl_add_u64 v[0:1], v[0:1], 0, v[34:35]
	v_lshl_add_u64 v[2:3], s[52:53], 0, v[32:33]
	s_add_u32 s44, s52, s43
	v_lshl_add_u64 v[2:3], v[2:3], 0, v[34:35]
	global_load_dwordx4 v[50:53], v[0:1], off offset:1536
	global_load_dwordx4 v[46:49], v[2:3], off offset:1536
	v_med3_i32 v0, s26, 0, v243
	s_addc_u32 s45, s53, 0
	s_max_i32 s43, s39, -9
	v_or_b32_e32 v0, s51, v0
	v_med3_i32 v2, s27, 0, v243
	s_add_i32 s43, s43, 9
	v_lshlrev_b32_e32 v32, 11, v0
	v_or_b32_e32 v2, s51, v2
	s_min_u32 s43, s43, 0x7ff
	v_lshl_add_u64 v[0:1], s[52:53], 0, v[32:33]
	v_lshlrev_b32_e32 v32, 11, v2
	s_or_b32 s43, s43, s51
	v_lshl_add_u64 v[0:1], v[0:1], 0, v[34:35]
	v_lshl_add_u64 v[2:3], s[52:53], 0, v[32:33]
	s_lshl_b32 s43, s43, 11
	v_lshl_add_u64 v[2:3], v[2:3], 0, v[34:35]
	global_load_dwordx4 v[58:61], v[0:1], off offset:1536
	global_load_dwordx4 v[54:57], v[2:3], off offset:1536
	v_lshl_add_u64 v[0:1], s[44:45], 0, v[34:35]
	s_add_u32 s44, s52, s43
	s_addc_u32 s45, s53, 0
	s_max_i32 s43, s39, -10
	s_add_i32 s43, s43, 10
	s_min_u32 s43, s43, 0x7ff
	s_or_b32 s43, s43, s51
	s_lshl_b32 s43, s43, 11
	v_lshl_add_u64 v[2:3], s[44:45], 0, v[34:35]
	s_add_u32 s44, s52, s43
	s_addc_u32 s45, s53, 0
	s_max_i32 s43, s39, -11
	s_add_i32 s43, s43, 11
	s_min_u32 s43, s43, 0x7ff
	s_or_b32 s43, s43, s51
	s_lshl_b32 s43, s43, 11
	global_load_dwordx4 v[24:27], v[0:1], off offset:1536
	global_load_dwordx4 v[20:23], v[2:3], off offset:1536
	v_lshl_add_u64 v[0:1], s[44:45], 0, v[34:35]
	s_add_u32 s44, s52, s43
	s_addc_u32 s45, s53, 0
	s_max_i32 s43, s39, -12
	s_add_i32 s43, s43, 12
	s_min_u32 s43, s43, 0x7ff
	s_or_b32 s43, s43, s51
	s_lshl_b32 s43, s43, 11
	v_lshl_add_u64 v[2:3], s[44:45], 0, v[34:35]
	s_add_u32 s44, s52, s43
	s_addc_u32 s45, s53, 0
	s_max_i32 s43, s39, -13
	s_add_i32 s43, s43, 13
	s_min_u32 s43, s43, 0x7ff
	s_or_b32 s43, s43, s51
	s_lshl_b32 s43, s43, 11
	global_load_dwordx4 v[16:19], v[0:1], off offset:1536
	global_load_dwordx4 v[12:15], v[2:3], off offset:1536
	v_lshl_add_u64 v[0:1], s[44:45], 0, v[34:35]
	s_add_u32 s44, s52, s43
	s_addc_u32 s45, s53, 0
	s_max_i32 s43, s39, -14
	s_add_i32 s43, s43, 14
	s_min_u32 s43, s43, 0x7ff
	v_lshlrev_b32_e64 v32, v37, 1
	s_or_b32 s43, s43, s51
	v_sub_u32_e32 v37, s39, v32
	v_add_u32_e32 v98, s39, v32
	s_lshl_b32 s43, s43, 11
	v_max_i32_e32 v37, 0, v37
	v_min_i32_e32 v103, 0x800, v98
	v_lshl_add_u64 v[2:3], s[44:45], 0, v[34:35]
	s_add_u32 s44, s52, s43
	v_cmp_ge_i32_e32 vcc, s42, v37
	v_cmp_lt_i32_e64 s[42:43], s42, v103
	s_addc_u32 s45, s53, 0
	s_and_b64 s[42:43], vcc, s[42:43]
	v_cndmask_b32_e64 v102, 0, 1.0, s[42:43]
	v_cmp_ge_i32_e32 vcc, s50, v37
	v_cmp_lt_i32_e64 s[42:43], s50, v103
	s_and_b64 s[42:43], vcc, s[42:43]
	v_cmp_ge_i32_e32 vcc, s49, v37
	v_cndmask_b32_e64 v106, 0, 1.0, s[42:43]
	v_cmp_lt_i32_e64 s[42:43], s49, v103
	s_and_b64 s[42:43], vcc, s[42:43]
	v_cmp_ge_i32_e32 vcc, s48, v37
	v_cndmask_b32_e64 v108, 0, 1.0, s[42:43]
	v_cmp_lt_i32_e64 s[42:43], s48, v103
	s_and_b64 s[42:43], vcc, s[42:43]
	v_cmp_ge_i32_e32 vcc, s31, v37
	v_cndmask_b32_e64 v110, 0, 1.0, s[42:43]
	v_cmp_lt_i32_e64 s[42:43], s31, v103
	v_writelane_b32 v200, s26, 0
	v_writelane_b32 v200, s27, 1
	v_writelane_b32 v200, s30, 2
	v_writelane_b32 v200, s31, 3
	v_writelane_b32 v200, s34, 4
	v_writelane_b32 v200, s35, 5
	v_writelane_b32 v200, s40, 6
	v_writelane_b32 v200, s41, 7
	v_writelane_b32 v200, s42, 8
	v_writelane_b32 v200, s43, 9
	v_writelane_b32 v200, s44, 10
	v_writelane_b32 v200, s45, 11
	v_writelane_b32 v200, s46, 12
	v_writelane_b32 v200, s47, 13
	v_writelane_b32 v200, s48, 14
	v_writelane_b32 v200, s49, 15
	v_writelane_b32 v200, s50, 16
	v_writelane_b32 v200, s51, 17
	s_mov_b64 s[98:99], exec
	s_mov_b64 exec, s[24:25]
	s_max_i32 s26, s39, 1
	s_add_i32 s26, s26, -1
	s_min_u32 s26, s26, 0x7ff
	v_readlane_b32 s34, v253, 4
	s_or_b32 s26, s26, s34
	v_lshlrev_b32_e32 v8, 3, v1
	s_lshl_b32 s26, s26, 11
	v_readlane_b32 s58, v252, 5
	v_ashrrev_i32_e32 v9, 31, v8
	v_readlane_b32 s59, v252, 6
	s_add_u32 s26, s58, s26
	s_addc_u32 s27, s59, 0
	v_lshlrev_b64 v[34:35], 1, v[8:9]
	v_lshl_add_u64 v[2:3], s[26:27], 0, v[34:35]
	s_max_i32 s26, s39, -1
	s_add_i32 s26, s26, 1
	s_min_u32 s26, s26, 0x7ff
	v_or_b32_e32 v0, s34, v0
	s_or_b32 s26, s26, s34
	v_lshlrev_b32_e32 v32, 11, v0
	s_lshl_b32 s26, s26, 11
	v_lshl_add_u64 v[0:1], s[58:59], 0, v[32:33]
	s_add_u32 s26, s58, s26
	v_lshl_add_u64 v[0:1], v[0:1], 0, v[34:35]
	s_addc_u32 s27, s59, 0
	global_load_dwordx4 v[130:133], v[2:3], off
	global_load_dwordx4 v[122:125], v[2:3], off offset:1024
	global_load_dwordx4 v[118:121], v[0:1], off
	global_load_dwordx4 v[110:113], v[0:1], off offset:1024
	v_lshl_add_u64 v[0:1], s[26:27], 0, v[34:35]
	s_or_b32 s57, s39, 2
	global_load_dwordx4 v[114:117], v[0:1], off
	global_load_dwordx4 v[106:109], v[0:1], off offset:1024
	v_med3_i32 v0, s57, 0, v243
	v_or_b32_e32 v0, s34, v0
	v_lshlrev_b32_e32 v32, 11, v0
	v_lshl_add_u64 v[0:1], s[58:59], 0, v[32:33]
	v_lshl_add_u64 v[0:1], v[0:1], 0, v[34:35]
	s_or_b32 s56, s39, 3
	global_load_dwordx4 v[102:105], v[0:1], off
	global_load_dwordx4 v[98:101], v[0:1], off offset:1024
	v_med3_i32 v0, s56, 0, v243
	v_or_b32_e32 v0, s34, v0
	v_lshlrev_b32_e32 v32, 11, v0
	v_lshl_add_u64 v[0:1], s[58:59], 0, v[32:33]
	v_lshl_add_u64 v[0:1], v[0:1], 0, v[34:35]
	s_or_b32 s41, s39, 4
	global_load_dwordx4 v[90:93], v[0:1], off
	global_load_dwordx4 v[82:85], v[0:1], off offset:1024
	v_med3_i32 v0, s41, 0, v243
	v_or_b32_e32 v0, s34, v0
	v_lshlrev_b32_e32 v32, 11, v0
	v_lshl_add_u64 v[0:1], s[58:59], 0, v[32:33]
	v_lshl_add_u64 v[0:1], v[0:1], 0, v[34:35]
	s_or_b32 s40, s39, 5
	global_load_dwordx4 v[78:81], v[0:1], off
	global_load_dwordx4 v[74:77], v[0:1], off offset:1024
	v_med3_i32 v0, s40, 0, v243
	v_or_b32_e32 v0, s34, v0
	v_lshlrev_b32_e32 v32, 11, v0
	v_lshl_add_u64 v[0:1], s[58:59], 0, v[32:33]
	v_lshl_add_u64 v[0:1], v[0:1], 0, v[34:35]
	s_or_b32 s31, s39, 6
	global_load_dwordx4 v[66:69], v[0:1], off
	global_load_dwordx4 v[62:65], v[0:1], off offset:1024
	v_med3_i32 v0, s31, 0, v243
	s_max_i32 s26, s39, -8
	v_or_b32_e32 v0, s34, v0
	s_add_i32 s26, s26, 8
	v_lshlrev_b32_e32 v32, 11, v0
	s_min_u32 s26, s26, 0x7ff
	v_lshl_add_u64 v[0:1], s[58:59], 0, v[32:33]
	s_or_b32 s26, s26, s34
	v_lshl_add_u64 v[0:1], v[0:1], 0, v[34:35]
	s_or_b32 s30, s39, 7
	s_lshl_b32 s26, s26, 11
	global_load_dwordx4 v[54:57], v[0:1], off
	global_load_dwordx4 v[50:53], v[0:1], off offset:1024
	v_med3_i32 v0, s30, 0, v243
	v_readlane_b32 s42, v255, 35
	s_add_u32 s26, s58, s26
	v_or_b32_e32 v0, s34, v0
	v_readlane_b32 s43, v255, 36
	s_addc_u32 s27, s59, 0
	v_lshlrev_b32_e32 v32, 11, v0
	v_lshl_add_u64 v[42:43], v[8:9], 2, s[42:43]
	v_lshl_add_u64 v[8:9], s[26:27], 0, v[34:35]
	s_add_i32 s26, s39, s34
	v_lshl_add_u64 v[0:1], s[58:59], 0, v[32:33]
	s_ashr_i32 s27, s26, 31
	v_lshl_add_u64 v[0:1], v[0:1], 0, v[34:35]
	s_lshl_b64 s[54:55], s[26:27], 11
	global_load_dwordx4 v[4:7], v[0:1], off
	s_nop 0
	global_load_dwordx4 v[0:3], v[0:1], off offset:1024
	s_nop 0
	global_load_dwordx4 v[16:19], v[42:43], off offset:16
	global_load_dwordx4 v[28:31], v[42:43], off
	s_add_u32 s34, s58, s54
	global_load_dwordx4 v[12:15], v[8:9], off
	s_nop 0
	global_load_dwordx4 v[8:11], v[8:9], off offset:1024
	s_nop 0
	global_load_dwordx4 v[20:23], v[42:43], off offset:1040
	global_load_dwordx4 v[38:41], v[42:43], off offset:1024
	s_addc_u32 s35, s59, s55
	global_load_dwordx4 v[24:27], v[42:43], off offset:2064
	global_load_dwordx4 v[46:49], v[42:43], off offset:2048
	v_lshl_add_u64 v[42:43], s[34:35], 0, v[34:35]
	global_load_dwordx4 v[138:141], v[42:43], off offset:512
	s_or_b32 s34, s26, 1
	s_ashr_i32 s35, s34, 31
	s_lshl_b64 s[52:53], s[34:35], 11
	s_add_u32 s34, s58, s52
	s_addc_u32 s35, s59, s53
	v_lshl_add_u64 v[42:43], s[34:35], 0, v[34:35]
	global_load_dwordx4 v[134:137], v[42:43], off offset:512
	s_or_b32 s34, s26, 2
	s_ashr_i32 s35, s34, 31
	s_lshl_b64 s[50:51], s[34:35], 11
	s_add_u32 s34, s58, s50
	s_addc_u32 s35, s59, s51
	v_lshl_add_u64 v[42:43], s[34:35], 0, v[34:35]
	s_or_b32 s34, s26, 3
	s_ashr_i32 s35, s34, 31
	s_lshl_b64 s[48:49], s[34:35], 11
	s_add_u32 s34, s58, s48
	s_addc_u32 s35, s59, s49
	v_lshl_add_u64 v[44:45], s[34:35], 0, v[34:35]
	global_load_dwordx4 v[126:129], v[42:43], off offset:512
	global_load_dwordx4 v[94:97], v[44:45], off offset:512
	s_or_b32 s34, s26, 4
	s_ashr_i32 s35, s34, 31
	s_lshl_b64 s[44:45], s[34:35], 11
	s_add_u32 s34, s58, s44
	s_addc_u32 s35, s59, s45
	v_lshl_add_u64 v[42:43], s[34:35], 0, v[34:35]
	s_or_b32 s34, s26, 5
	s_ashr_i32 s35, s34, 31
	s_lshl_b64 s[42:43], s[34:35], 11
	s_add_u32 s34, s58, s42
	s_addc_u32 s35, s59, s43
	v_lshl_add_u64 v[44:45], s[34:35], 0, v[34:35]
	s_or_b32 s34, s26, 6
	s_ashr_i32 s35, s34, 31
	s_lshl_b64 s[34:35], s[34:35], 11
	s_add_u32 s46, s58, s34
	s_addc_u32 s47, s59, s35
	s_or_b32 s26, s26, 7
	s_ashr_i32 s27, s26, 31
	s_lshl_b64 s[26:27], s[26:27], 11
	global_load_dwordx4 v[86:89], v[42:43], off offset:512
	global_load_dwordx4 v[70:73], v[44:45], off offset:512
	v_lshl_add_u64 v[42:43], s[46:47], 0, v[34:35]
	s_add_u32 s46, s58, s26
	s_addc_u32 s47, s59, s27
	v_lshl_add_u64 v[44:45], s[46:47], 0, v[34:35]
	v_readlane_b32 s46, v252, 7
	v_readlane_b32 s47, v252, 8
	v_writelane_b32 v201, s26, 0
	v_writelane_b32 v201, s27, 1
	v_writelane_b32 v201, s30, 2
	v_writelane_b32 v201, s31, 3
	v_writelane_b32 v201, s34, 4
	v_writelane_b32 v201, s35, 5
	v_writelane_b32 v201, s40, 6
	v_writelane_b32 v201, s41, 7
	v_writelane_b32 v201, s42, 8
	v_writelane_b32 v201, s43, 9
	v_writelane_b32 v201, s44, 10
	v_writelane_b32 v201, s45, 11
	v_writelane_b32 v201, s46, 12
	v_writelane_b32 v201, s47, 13
	v_writelane_b32 v201, s48, 14
	v_writelane_b32 v201, s49, 15
	v_writelane_b32 v201, s50, 16
	v_writelane_b32 v201, s51, 17
	v_writelane_b32 v201, s52, 18
	v_writelane_b32 v201, s53, 19
	v_writelane_b32 v201, s54, 20
	v_writelane_b32 v201, s55, 21
	v_writelane_b32 v201, s56, 22
	v_writelane_b32 v201, s57, 23
	s_mov_b64 exec, s[98:99]
	v_readlane_b32 s26, v200, 0
	v_readlane_b32 s27, v200, 1
	v_readlane_b32 s30, v200, 2
	v_readlane_b32 s31, v200, 3
	v_readlane_b32 s34, v200, 4
	v_readlane_b32 s35, v200, 5
	v_readlane_b32 s40, v200, 6
	v_readlane_b32 s41, v200, 7
	v_readlane_b32 s42, v200, 8
	v_readlane_b32 s43, v200, 9
	v_readlane_b32 s44, v200, 10
	v_readlane_b32 s45, v200, 11
	v_readlane_b32 s46, v200, 12
	v_readlane_b32 s47, v200, 13
	v_readlane_b32 s48, v200, 14
	v_readlane_b32 s49, v200, 15
	v_readlane_b32 s50, v200, 16
	v_readlane_b32 s51, v200, 17
	s_nop 4
	s_waitcnt vmcnt(51)
	v_and_b32_e32 v99, 0xffff0000, v66
	v_lshlrev_b32_e32 v98, 16, v66
	s_and_b64 s[42:43], vcc, s[42:43]
	v_pk_fma_f32 v[98:99], v[102:103], v[98:99], 0 op_sel_hi:[0,1,0]
	s_waitcnt vmcnt(50)
	v_and_b32_e32 v153, 0xffff0000, v62
	v_lshlrev_b32_e32 v152, 16, v62
	v_cndmask_b32_e64 v112, 0, 1.0, s[42:43]
	v_cmp_ge_i32_e32 vcc, s30, v37
	v_cmp_lt_i32_e64 s[42:43], s30, v103
	v_pk_fma_f32 v[98:99], v[106:107], v[152:153], v[98:99] op_sel_hi:[0,1,1]
	s_waitcnt vmcnt(49)
	v_and_b32_e32 v131, 0xffff0000, v82
	v_lshlrev_b32_e32 v130, 16, v82
	s_and_b64 s[42:43], vcc, s[42:43]
	v_pk_fma_f32 v[98:99], v[108:109], v[130:131], v[98:99] op_sel_hi:[0,1,1]
	s_waitcnt vmcnt(48)
	v_and_b32_e32 v141, 0xffff0000, v70
	v_lshlrev_b32_e32 v140, 16, v70
	v_cndmask_b32_e64 v114, 0, 1.0, s[42:43]
	v_cmp_ge_i32_e32 vcc, s47, v37
	v_cmp_lt_i32_e64 s[42:43], s47, v103
	v_pk_fma_f32 v[98:99], v[110:111], v[140:141], v[98:99] op_sel_hi:[0,1,1]
	s_waitcnt vmcnt(47)
	v_and_b32_e32 v129, 0xffff0000, v90
	v_lshlrev_b32_e32 v128, 16, v90
	s_and_b64 s[42:43], vcc, s[42:43]
	v_pk_fma_f32 v[98:99], v[112:113], v[128:129], v[98:99] op_sel_hi:[0,1,1]
	s_waitcnt vmcnt(46)
	v_and_b32_e32 v121, 0xffff0000, v86
	v_lshlrev_b32_e32 v120, 16, v86
	v_cndmask_b32_e64 v116, 0, 1.0, s[42:43]
	v_pk_fma_f32 v[100:101], v[114:115], v[120:121], v[98:99] op_sel_hi:[0,1,1]
	s_waitcnt vmcnt(45)
	v_and_b32_e32 v99, 0xffff0000, v94
	v_lshlrev_b32_e32 v98, 16, v94
	v_pk_fma_f32 v[118:119], v[116:117], v[98:99], v[100:101] op_sel_hi:[0,1,1]
	v_and_b32_e32 v101, 0xffff0000, v67
	v_lshlrev_b32_e32 v100, 16, v67
	v_pk_fma_f32 v[66:67], v[102:103], v[100:101], 0 op_sel_hi:[0,1,0]
	v_and_b32_e32 v155, 0xffff0000, v63
	v_lshlrev_b32_e32 v154, 16, v63
	v_pk_fma_f32 v[62:63], v[106:107], v[154:155], v[66:67] op_sel_hi:[0,1,1]
	v_and_b32_e32 v133, 0xffff0000, v83
	v_lshlrev_b32_e32 v132, 16, v83
	v_pk_fma_f32 v[62:63], v[108:109], v[132:133], v[62:63] op_sel_hi:[0,1,1]
	v_and_b32_e32 v143, 0xffff0000, v71
	v_lshlrev_b32_e32 v142, 16, v71
	v_pk_fma_f32 v[62:63], v[110:111], v[142:143], v[62:63] op_sel_hi:[0,1,1]
	v_and_b32_e32 v135, 0xffff0000, v91
	v_lshlrev_b32_e32 v134, 16, v91
	v_pk_fma_f32 v[62:63], v[112:113], v[134:135], v[62:63] op_sel_hi:[0,1,1]
	v_and_b32_e32 v123, 0xffff0000, v87
	v_lshlrev_b32_e32 v122, 16, v87
	v_pk_fma_f32 v[62:63], v[114:115], v[122:123], v[62:63] op_sel_hi:[0,1,1]
	v_and_b32_e32 v101, 0xffff0000, v95
	v_lshlrev_b32_e32 v100, 16, v95
	v_pk_fma_f32 v[94:95], v[116:117], v[100:101], v[62:63] op_sel_hi:[0,1,1]
	v_and_b32_e32 v63, 0xffff0000, v68
	v_lshlrev_b32_e32 v62, 16, v68
	v_pk_fma_f32 v[62:63], v[102:103], v[62:63], 0 op_sel_hi:[0,1,0]
	v_and_b32_e32 v157, 0xffff0000, v64
	v_lshlrev_b32_e32 v156, 16, v64
	v_pk_fma_f32 v[62:63], v[106:107], v[156:157], v[62:63] op_sel_hi:[0,1,1]
	v_and_b32_e32 v149, 0xffff0000, v84
	v_lshlrev_b32_e32 v148, 16, v84
	v_pk_fma_f32 v[62:63], v[108:109], v[148:149], v[62:63] op_sel_hi:[0,1,1]
	v_and_b32_e32 v145, 0xffff0000, v72
	v_lshlrev_b32_e32 v144, 16, v72
	v_pk_fma_f32 v[62:63], v[110:111], v[144:145], v[62:63] op_sel_hi:[0,1,1]
	v_and_b32_e32 v137, 0xffff0000, v92
	v_lshlrev_b32_e32 v136, 16, v92
	v_pk_fma_f32 v[62:63], v[112:113], v[136:137], v[62:63] op_sel_hi:[0,1,1]
	v_and_b32_e32 v125, 0xffff0000, v88
	v_lshlrev_b32_e32 v124, 16, v88
	v_pk_fma_f32 v[62:63], v[114:115], v[124:125], v[62:63] op_sel_hi:[0,1,1]
	v_and_b32_e32 v105, 0xffff0000, v96
	v_lshlrev_b32_e32 v104, 16, v96
	v_pk_fma_f32 v[160:161], v[116:117], v[104:105], v[62:63] op_sel_hi:[0,1,1]
	v_and_b32_e32 v63, 0xffff0000, v69
	v_lshlrev_b32_e32 v62, 16, v69
	v_pk_fma_f32 v[62:63], v[102:103], v[62:63], 0 op_sel_hi:[0,1,0]
	v_and_b32_e32 v159, 0xffff0000, v65
	v_lshlrev_b32_e32 v158, 16, v65
	v_pk_fma_f32 v[62:63], v[106:107], v[158:159], v[62:63] op_sel_hi:[0,1,1]
	v_and_b32_e32 v151, 0xffff0000, v85
	v_lshlrev_b32_e32 v150, 16, v85
	v_pk_fma_f32 v[62:63], v[108:109], v[150:151], v[62:63] op_sel_hi:[0,1,1]
	v_and_b32_e32 v147, 0xffff0000, v73
	v_lshlrev_b32_e32 v146, 16, v73
	v_pk_fma_f32 v[62:63], v[110:111], v[146:147], v[62:63] op_sel_hi:[0,1,1]
	v_and_b32_e32 v139, 0xffff0000, v93
	v_lshlrev_b32_e32 v138, 16, v93
	v_pk_fma_f32 v[62:63], v[112:113], v[138:139], v[62:63] op_sel_hi:[0,1,1]
	v_and_b32_e32 v127, 0xffff0000, v89
	v_lshlrev_b32_e32 v126, 16, v89
	v_cmp_gt_i32_e32 vcc, s39, v37
	v_cmp_le_i32_e64 s[42:43], s39, v103
	v_pk_fma_f32 v[62:63], v[114:115], v[126:127], v[62:63] op_sel_hi:[0,1,1]
	v_and_b32_e32 v113, 0xffff0000, v97
	v_lshlrev_b32_e32 v112, 16, v97
	s_and_b64 s[42:43], vcc, s[42:43]
	v_pk_fma_f32 v[114:115], v[116:117], v[112:113], v[62:63] op_sel_hi:[0,1,1]
	v_cndmask_b32_e64 v116, 0, 1.0, s[42:43]
	v_cmp_ge_i32_e32 vcc, s39, v37
	v_cmp_lt_i32_e64 s[42:43], s39, v103
	s_and_b64 s[42:43], vcc, s[42:43]
	v_cmp_ge_i32_e32 vcc, s34, v37
	v_cndmask_b32_e64 v162, 0, 1.0, s[42:43]
	v_cmp_lt_i32_e64 s[42:43], s34, v103
	s_and_b64 s[42:43], vcc, s[42:43]
	v_cmp_ge_i32_e32 vcc, s35, v37
	v_cndmask_b32_e64 v164, 0, 1.0, s[42:43]
	v_cmp_lt_i32_e64 s[42:43], s35, v103
	s_and_b64 s[42:43], vcc, s[42:43]
	v_cmp_ge_i32_e32 vcc, s40, v37
	v_cndmask_b32_e64 v166, 0, 1.0, s[42:43]
	v_cmp_lt_i32_e64 s[42:43], s40, v103
	s_and_b64 s[42:43], vcc, s[42:43]
	v_cmp_ge_i32_e32 vcc, s41, v37
	v_cndmask_b32_e64 v168, 0, 1.0, s[42:43]
	v_cmp_lt_i32_e64 s[42:43], s41, v103
	s_and_b64 s[42:43], vcc, s[42:43]
	v_sub_u32_e32 v72, v103, v37
	v_cndmask_b32_e64 v170, 0, 1.0, s[42:43]
	v_cmp_ge_i32_e32 vcc, s46, v37
	v_cmp_lt_i32_e64 s[42:43], s46, v103
	v_cvt_f32_i32_e32 v72, v72
	s_and_b64 s[42:43], vcc, s[42:43]
	v_cndmask_b32_e64 v172, 0, 1.0, s[42:43]
	v_cmp_ge_i32_e32 vcc, s26, v37
	v_cmp_lt_i32_e64 s[42:43], s26, v103
	s_and_b64 s[42:43], vcc, s[42:43]
	v_cmp_ge_i32_e32 vcc, s27, v37
	v_cndmask_b32_e64 v174, 0, 1.0, s[42:43]
	v_div_scale_f32 v37, s[42:43], v72, v72, 1.0
	v_rcp_f32_e32 v73, v37
	s_waitcnt vmcnt(44)
	v_and_b32_e32 v69, 0xffff0000, v78
	v_lshlrev_b32_e32 v68, 16, v78
	v_and_b32_e32 v67, 0xffff0000, v79
	v_lshlrev_b32_e32 v66, 16, v79
	v_and_b32_e32 v65, 0xffff0000, v80
	v_lshlrev_b32_e32 v64, 16, v80
	v_and_b32_e32 v63, 0xffff0000, v81
	v_lshlrev_b32_e32 v62, 16, v81
	s_waitcnt vmcnt(42)
	v_and_b32_e32 v81, 0xffff0000, v74
	v_lshlrev_b32_e32 v80, 16, v74
	v_and_b32_e32 v79, 0xffff0000, v75
	v_lshlrev_b32_e32 v78, 16, v75
	v_and_b32_e32 v75, 0xffff0000, v76
	v_lshlrev_b32_e32 v74, 16, v76
	v_cmp_lt_i32_e64 s[42:43], s27, v103
	v_fma_f32 v76, -v37, v73, 1.0
	s_and_b64 s[42:43], vcc, s[42:43]
	v_fmac_f32_e32 v73, v76, v73
	v_div_scale_f32 v76, vcc, 1.0, v72, 1.0
	v_and_b32_e32 v71, 0xffff0000, v77
	v_lshlrev_b32_e32 v70, 16, v77
	v_mul_f32_e32 v77, v76, v73
	v_fma_f32 v82, -v37, v77, v76
	v_fmac_f32_e32 v77, v82, v73
	v_fma_f32 v37, -v37, v77, v76
	v_div_fmas_f32 v37, v37, v73, v77
	v_div_fixup_f32 v178, v37, v72, 1.0
	v_pk_fma_f32 v[72:73], v[116:117], v[68:69], v[118:119] op_sel_hi:[0,1,1]
	v_and_b32_e32 v83, 0xffff0000, v28
	v_lshlrev_b32_e32 v82, 16, v28
	v_pk_fma_f32 v[72:73], v[162:163], v[82:83], v[72:73] op_sel_hi:[0,1,1]
	v_pk_fma_f32 v[72:73], v[164:165], v[80:81], v[72:73] op_sel_hi:[0,1,1]
	s_waitcnt vmcnt(41)
	v_and_b32_e32 v85, 0xffff0000, v42
	v_lshlrev_b32_e32 v84, 16, v42
	v_pk_fma_f32 v[72:73], v[166:167], v[84:85], v[72:73] op_sel_hi:[0,1,1]
	s_waitcnt vmcnt(40)
	v_and_b32_e32 v87, 0xffff0000, v38
	v_lshlrev_b32_e32 v86, 16, v38
	v_pk_fma_f32 v[72:73], v[168:169], v[86:87], v[72:73] op_sel_hi:[0,1,1]
	s_waitcnt vmcnt(39)
	v_and_b32_e32 v89, 0xffff0000, v50
	v_lshlrev_b32_e32 v88, 16, v50
	v_pk_fma_f32 v[72:73], v[170:171], v[88:89], v[72:73] op_sel_hi:[0,1,1]
	s_waitcnt vmcnt(38)
	v_and_b32_e32 v91, 0xffff0000, v46
	v_lshlrev_b32_e32 v90, 16, v46
	v_pk_fma_f32 v[72:73], v[172:173], v[90:91], v[72:73] op_sel_hi:[0,1,1]
	s_waitcnt vmcnt(37)
	v_and_b32_e32 v77, 0xffff0000, v58
	v_lshlrev_b32_e32 v76, 16, v58
	v_cndmask_b32_e64 v176, 0, 1.0, s[42:43]
	v_pk_fma_f32 v[92:93], v[174:175], v[76:77], v[72:73] op_sel_hi:[0,1,1]
	s_waitcnt vmcnt(36)
	v_and_b32_e32 v73, 0xffff0000, v54
	v_lshlrev_b32_e32 v72, 16, v54
	v_pk_fma_f32 v[92:93], v[176:177], v[72:73], v[92:93] op_sel_hi:[0,1,1]
	v_pk_fma_f32 v[184:185], v[178:179], v[92:93], v[82:83] op_sel_hi:[0,1,1] neg_lo:[0,0,1] neg_hi:[0,0,1]
	v_pk_fma_f32 v[94:95], v[116:117], v[66:67], v[94:95] op_sel_hi:[0,1,1]
	v_and_b32_e32 v93, 0xffff0000, v29
	v_lshlrev_b32_e32 v92, 16, v29
	v_pk_fma_f32 v[28:29], v[162:163], v[92:93], v[94:95] op_sel_hi:[0,1,1]
	v_pk_fma_f32 v[28:29], v[164:165], v[78:79], v[28:29] op_sel_hi:[0,1,1]
	v_and_b32_e32 v95, 0xffff0000, v43
	v_lshlrev_b32_e32 v94, 16, v43
	v_pk_fma_f32 v[28:29], v[166:167], v[94:95], v[28:29] op_sel_hi:[0,1,1]
	v_and_b32_e32 v97, 0xffff0000, v39
	v_lshlrev_b32_e32 v96, 16, v39
	v_pk_fma_f32 v[28:29], v[168:169], v[96:97], v[28:29] op_sel_hi:[0,1,1]
	v_and_b32_e32 v103, 0xffff0000, v51
	v_lshlrev_b32_e32 v102, 16, v51
	v_pk_fma_f32 v[28:29], v[170:171], v[102:103], v[28:29] op_sel_hi:[0,1,1]
	v_and_b32_e32 v51, 0xffff0000, v47
	v_lshlrev_b32_e32 v50, 16, v47
	v_pk_fma_f32 v[28:29], v[172:173], v[50:51], v[28:29] op_sel_hi:[0,1,1]
	v_and_b32_e32 v39, 0xffff0000, v59
	v_lshlrev_b32_e32 v38, 16, v59
	v_pk_fma_f32 v[42:43], v[174:175], v[38:39], v[28:29] op_sel_hi:[0,1,1]
	v_and_b32_e32 v29, 0xffff0000, v55
	v_lshlrev_b32_e32 v28, 16, v55
	v_pk_fma_f32 v[42:43], v[176:177], v[28:29], v[42:43] op_sel_hi:[0,1,1]
	v_pk_fma_f32 v[186:187], v[178:179], v[42:43], v[92:93] op_sel_hi:[0,1,1] neg_lo:[0,0,1] neg_hi:[0,0,1]
	v_pk_fma_f32 v[42:43], v[116:117], v[64:65], v[160:161] op_sel_hi:[0,1,1]
	v_and_b32_e32 v55, 0xffff0000, v30
	v_lshlrev_b32_e32 v54, 16, v30
	v_pk_fma_f32 v[42:43], v[162:163], v[54:55], v[42:43] op_sel_hi:[0,1,1]
	v_pk_fma_f32 v[42:43], v[164:165], v[74:75], v[42:43] op_sel_hi:[0,1,1]
	v_and_b32_e32 v59, 0xffff0000, v44
	v_lshlrev_b32_e32 v58, 16, v44
	v_pk_fma_f32 v[42:43], v[166:167], v[58:59], v[42:43] op_sel_hi:[0,1,1]
	v_and_b32_e32 v107, 0xffff0000, v40
	v_lshlrev_b32_e32 v106, 16, v40
	v_pk_fma_f32 v[42:43], v[168:169], v[106:107], v[42:43] op_sel_hi:[0,1,1]
	v_and_b32_e32 v109, 0xffff0000, v52
	v_lshlrev_b32_e32 v108, 16, v52
	v_pk_fma_f32 v[42:43], v[170:171], v[108:109], v[42:43] op_sel_hi:[0,1,1]
	v_and_b32_e32 v111, 0xffff0000, v48
	v_lshlrev_b32_e32 v110, 16, v48
	v_pk_fma_f32 v[116:117], v[116:117], v[62:63], v[114:115] op_sel_hi:[0,1,1]
	v_and_b32_e32 v115, 0xffff0000, v31
	v_lshlrev_b32_e32 v114, 16, v31
	v_pk_fma_f32 v[42:43], v[172:173], v[110:111], v[42:43] op_sel_hi:[0,1,1]
	v_and_b32_e32 v47, 0xffff0000, v60
	v_lshlrev_b32_e32 v46, 16, v60
	v_pk_fma_f32 v[30:31], v[162:163], v[114:115], v[116:117] op_sel_hi:[0,1,1]
	v_pk_fma_f32 v[118:119], v[174:175], v[46:47], v[42:43] op_sel_hi:[0,1,1]
	v_and_b32_e32 v43, 0xffff0000, v56
	v_lshlrev_b32_e32 v42, 16, v56
	v_pk_fma_f32 v[30:31], v[164:165], v[70:71], v[30:31] op_sel_hi:[0,1,1]
	v_and_b32_e32 v117, 0xffff0000, v45
	v_lshlrev_b32_e32 v116, 16, v45
	v_pk_fma_f32 v[118:119], v[176:177], v[42:43], v[118:119] op_sel_hi:[0,1,1]
	v_pk_fma_f32 v[30:31], v[166:167], v[116:117], v[30:31] op_sel_hi:[0,1,1]
	v_and_b32_e32 v45, 0xffff0000, v41
	v_lshlrev_b32_e32 v44, 16, v41
	v_pk_fma_f32 v[188:189], v[178:179], v[118:119], v[54:55] op_sel_hi:[0,1,1] neg_lo:[0,0,1] neg_hi:[0,0,1]
	v_pk_fma_f32 v[30:31], v[168:169], v[44:45], v[30:31] op_sel_hi:[0,1,1]
	v_and_b32_e32 v119, 0xffff0000, v53
	v_lshlrev_b32_e32 v118, 16, v53
	global_load_dwordx4 v[8:11], v[0:1], off offset:1536
	global_load_dwordx4 v[4:7], v[2:3], off offset:1536
	v_lshl_add_u64 v[0:1], s[44:45], 0, v[34:35]
	s_add_i32 s44, s39, s51
	v_pk_fma_f32 v[30:31], v[170:171], v[118:119], v[30:31] op_sel_hi:[0,1,1]
	v_and_b32_e32 v53, 0xffff0000, v49
	v_lshlrev_b32_e32 v52, 16, v49
	v_pk_fma_f32 v[30:31], v[172:173], v[52:53], v[30:31] op_sel_hi:[0,1,1]
	v_and_b32_e32 v41, 0xffff0000, v61
	v_lshlrev_b32_e32 v40, 16, v61
	s_ashr_i32 s45, s44, 31
	v_pk_fma_f32 v[48:49], v[174:175], v[40:41], v[30:31] op_sel_hi:[0,1,1]
	v_and_b32_e32 v31, 0xffff0000, v57
	v_lshlrev_b32_e32 v30, 16, v57
	s_lshl_b64 s[42:43], s[44:45], 11
	v_readlane_b32 s52, v252, 7
	v_pk_fma_f32 v[48:49], v[176:177], v[30:31], v[48:49] op_sel_hi:[0,1,1]
	v_readlane_b32 s53, v252, 8
	s_add_u32 s42, s52, s42
	v_pk_fma_f32 v[48:49], v[178:179], v[48:49], v[114:115] op_sel_hi:[0,1,1] neg_lo:[0,0,1] neg_hi:[0,0,1]
	s_addc_u32 s43, s53, s43
	v_cvt_pk_bf16_f32 v160, v184, v185
	v_cvt_pk_bf16_f32 v161, v186, v187
	v_cvt_pk_bf16_f32 v162, v188, v189
	v_cvt_pk_bf16_f32 v163, v48, v49
	v_lshl_add_u64 v[48:49], s[42:43], 0, v[34:35]
	global_store_dwordx4 v[48:49], v[160:163], off offset:512
	v_sub_u32_e32 v37, s34, v32
	v_add_u32_e32 v48, s34, v32
	v_max_i32_e32 v37, 0, v37
	v_min_i32_e32 v57, 0x800, v48
	v_cmp_ge_i32_e32 vcc, s50, v37
	v_cmp_lt_i32_e64 s[42:43], s50, v57
	s_and_b64 s[42:43], vcc, s[42:43]
	v_cmp_ge_i32_e32 vcc, s49, v37
	v_cndmask_b32_e64 v48, 0, 1.0, s[42:43]
	v_cmp_lt_i32_e64 s[42:43], s49, v57
	s_and_b64 s[42:43], vcc, s[42:43]
	v_cmp_ge_i32_e32 vcc, s48, v37
	v_cndmask_b32_e64 v56, 0, 1.0, s[42:43]
	v_cmp_lt_i32_e64 s[42:43], s48, v57
	s_and_b64 s[42:43], vcc, s[42:43]
	v_cmp_ge_i32_e32 vcc, s31, v37
	v_cndmask_b32_e64 v60, 0, 1.0, s[42:43]
	v_cmp_lt_i32_e64 s[42:43], s31, v57
	s_and_b64 s[42:43], vcc, s[42:43]
	v_cmp_ge_i32_e32 vcc, s30, v37
	v_cndmask_b32_e64 v160, 0, 1.0, s[42:43]
	v_cmp_lt_i32_e64 s[42:43], s30, v57
	s_and_b64 s[42:43], vcc, s[42:43]
	v_cmp_ge_i32_e32 vcc, s47, v37
	v_cndmask_b32_e64 v162, 0, 1.0, s[42:43]
	v_cmp_lt_i32_e64 s[42:43], s47, v57
	s_and_b64 s[42:43], vcc, s[42:43]
	v_cmp_gt_i32_e32 vcc, s39, v37
	v_cndmask_b32_e64 v164, 0, 1.0, s[42:43]
	v_cmp_le_i32_e64 s[42:43], s39, v57
	s_and_b64 s[42:43], vcc, s[42:43]
	v_pk_fma_f32 v[152:153], v[48:49], v[152:153], 0 op_sel_hi:[0,1,0]
	v_pk_fma_f32 v[154:155], v[48:49], v[154:155], 0 op_sel_hi:[0,1,0]
	v_pk_fma_f32 v[156:157], v[48:49], v[156:157], 0 op_sel_hi:[0,1,0]
	v_pk_fma_f32 v[48:49], v[48:49], v[158:159], 0 op_sel_hi:[0,1,0]
	v_cndmask_b32_e64 v166, 0, 1.0, s[42:43]
	v_pk_fma_f32 v[152:153], v[56:57], v[130:131], v[152:153] op_sel_hi:[0,1,1]
	v_pk_fma_f32 v[154:155], v[56:57], v[132:133], v[154:155] op_sel_hi:[0,1,1]
	v_pk_fma_f32 v[156:157], v[56:57], v[148:149], v[156:157] op_sel_hi:[0,1,1]
	v_pk_fma_f32 v[48:49], v[56:57], v[150:151], v[48:49] op_sel_hi:[0,1,1]
	v_cmp_ge_i32_e32 vcc, s39, v37
	v_cmp_lt_i32_e64 s[42:43], s39, v57
	v_pk_fma_f32 v[152:153], v[60:61], v[140:141], v[152:153] op_sel_hi:[0,1,1]
	v_pk_fma_f32 v[154:155], v[60:61], v[142:143], v[154:155] op_sel_hi:[0,1,1]
	v_pk_fma_f32 v[156:157], v[60:61], v[144:145], v[156:157] op_sel_hi:[0,1,1]
	v_pk_fma_f32 v[48:49], v[60:61], v[146:147], v[48:49] op_sel_hi:[0,1,1]
	s_and_b64 s[42:43], vcc, s[42:43]
	v_pk_fma_f32 v[152:153], v[160:161], v[128:129], v[152:153] op_sel_hi:[0,1,1]
	v_pk_fma_f32 v[154:155], v[160:161], v[134:135], v[154:155] op_sel_hi:[0,1,1]
	v_pk_fma_f32 v[156:157], v[160:161], v[136:137], v[156:157] op_sel_hi:[0,1,1]
	v_pk_fma_f32 v[48:49], v[160:161], v[138:139], v[48:49] op_sel_hi:[0,1,1]
	v_cndmask_b32_e64 v160, 0, 1.0, s[42:43]
	v_cmp_ge_i32_e32 vcc, s34, v37
	v_cmp_lt_i32_e64 s[42:43], s34, v57
	s_and_b64 s[42:43], vcc, s[42:43]
	v_pk_fma_f32 v[152:153], v[162:163], v[120:121], v[152:153] op_sel_hi:[0,1,1]
	v_pk_fma_f32 v[154:155], v[162:163], v[122:123], v[154:155] op_sel_hi:[0,1,1]
	v_pk_fma_f32 v[156:157], v[162:163], v[124:125], v[156:157] op_sel_hi:[0,1,1]
	v_pk_fma_f32 v[48:49], v[162:163], v[126:127], v[48:49] op_sel_hi:[0,1,1]
	v_cndmask_b32_e64 v162, 0, 1.0, s[42:43]
	v_cmp_ge_i32_e32 vcc, s35, v37
	v_cmp_lt_i32_e64 s[42:43], s35, v57
	s_and_b64 s[42:43], vcc, s[42:43]
	v_pk_fma_f32 v[152:153], v[164:165], v[98:99], v[152:153] op_sel_hi:[0,1,1]
	v_pk_fma_f32 v[154:155], v[164:165], v[100:101], v[154:155] op_sel_hi:[0,1,1]
	v_pk_fma_f32 v[156:157], v[164:165], v[104:105], v[156:157] op_sel_hi:[0,1,1]
	v_pk_fma_f32 v[48:49], v[164:165], v[112:113], v[48:49] op_sel_hi:[0,1,1]
	v_cndmask_b32_e64 v164, 0, 1.0, s[42:43]
	v_cmp_ge_i32_e32 vcc, s40, v37
	v_cmp_lt_i32_e64 s[42:43], s40, v57
	s_and_b64 s[42:43], vcc, s[42:43]
	v_pk_fma_f32 v[152:153], v[166:167], v[68:69], v[152:153] op_sel_hi:[0,1,1]
	v_pk_fma_f32 v[154:155], v[166:167], v[66:67], v[154:155] op_sel_hi:[0,1,1]
	v_pk_fma_f32 v[156:157], v[166:167], v[64:65], v[156:157] op_sel_hi:[0,1,1]
	v_pk_fma_f32 v[158:159], v[166:167], v[62:63], v[48:49] op_sel_hi:[0,1,1]
	v_cndmask_b32_e64 v166, 0, 1.0, s[42:43]
	v_cmp_ge_i32_e32 vcc, s41, v37
	v_cmp_lt_i32_e64 s[42:43], s41, v57
	s_and_b64 s[42:43], vcc, s[42:43]
	v_cmp_ge_i32_e32 vcc, s46, v37
	v_cndmask_b32_e64 v168, 0, 1.0, s[42:43]
	v_cmp_lt_i32_e64 s[42:43], s46, v57
	s_and_b64 s[42:43], vcc, s[42:43]
	v_sub_u32_e32 v48, v57, v37
	v_cndmask_b32_e64 v170, 0, 1.0, s[42:43]
	v_cmp_ge_i32_e32 vcc, s26, v37
	v_cmp_lt_i32_e64 s[42:43], s26, v57
	v_cvt_f32_i32_e32 v48, v48
	s_and_b64 s[42:43], vcc, s[42:43]
	v_cndmask_b32_e64 v172, 0, 1.0, s[42:43]
	v_cmp_ge_i32_e32 vcc, s27, v37
	v_cmp_lt_i32_e64 s[42:43], s27, v57
	s_and_b64 s[42:43], vcc, s[42:43]
	s_add_i32 s45, s39, 8
	v_cndmask_b32_e64 v174, 0, 1.0, s[42:43]
	v_cmp_ge_i32_e32 vcc, s45, v37
	v_div_scale_f32 v37, s[42:43], v48, v48, 1.0
	v_rcp_f32_e32 v49, v37
	v_cmp_lt_i32_e64 s[42:43], s45, v57
	s_and_b64 s[42:43], vcc, s[42:43]
	s_waitcnt vmcnt(6)
	v_and_b32_e32 v61, 0xffff0000, v24
	v_fma_f32 v56, -v37, v49, 1.0
	v_fmac_f32_e32 v49, v56, v49
	v_div_scale_f32 v56, vcc, 1.0, v48, 1.0
	v_mul_f32_e32 v57, v56, v49
	v_fma_f32 v60, -v37, v57, v56
	v_fmac_f32_e32 v57, v60, v49
	v_fma_f32 v37, -v37, v57, v56
	v_div_fmas_f32 v37, v37, v49, v57
	v_div_fixup_f32 v178, v37, v48, 1.0
	v_pk_fma_f32 v[48:49], v[160:161], v[82:83], v[152:153] op_sel_hi:[0,1,1]
	v_pk_fma_f32 v[48:49], v[162:163], v[80:81], v[48:49] op_sel_hi:[0,1,1]
	v_pk_fma_f32 v[48:49], v[164:165], v[84:85], v[48:49] op_sel_hi:[0,1,1]
	v_pk_fma_f32 v[48:49], v[166:167], v[86:87], v[48:49] op_sel_hi:[0,1,1]
	v_pk_fma_f32 v[48:49], v[168:169], v[88:89], v[48:49] op_sel_hi:[0,1,1]
	v_pk_fma_f32 v[48:49], v[170:171], v[90:91], v[48:49] op_sel_hi:[0,1,1]
	v_pk_fma_f32 v[48:49], v[172:173], v[76:77], v[48:49] op_sel_hi:[0,1,1]
	v_cndmask_b32_e64 v176, 0, 1.0, s[42:43]
	v_pk_fma_f32 v[48:49], v[174:175], v[72:73], v[48:49] op_sel_hi:[0,1,1]
	v_lshlrev_b32_e32 v60, 16, v24
	v_pk_fma_f32 v[48:49], v[176:177], v[60:61], v[48:49] op_sel_hi:[0,1,1]
	v_pk_fma_f32 v[152:153], v[178:179], v[48:49], v[80:81] op_sel_hi:[0,1,1] neg_lo:[0,0,1] neg_hi:[0,0,1]
	v_pk_fma_f32 v[48:49], v[160:161], v[92:93], v[154:155] op_sel_hi:[0,1,1]
	v_pk_fma_f32 v[48:49], v[162:163], v[78:79], v[48:49] op_sel_hi:[0,1,1]
	v_pk_fma_f32 v[48:49], v[164:165], v[94:95], v[48:49] op_sel_hi:[0,1,1]
	v_pk_fma_f32 v[48:49], v[166:167], v[96:97], v[48:49] op_sel_hi:[0,1,1]
	v_pk_fma_f32 v[48:49], v[168:169], v[102:103], v[48:49] op_sel_hi:[0,1,1]
	v_pk_fma_f32 v[48:49], v[170:171], v[50:51], v[48:49] op_sel_hi:[0,1,1]
	v_pk_fma_f32 v[48:49], v[172:173], v[38:39], v[48:49] op_sel_hi:[0,1,1]
	v_pk_fma_f32 v[48:49], v[174:175], v[28:29], v[48:49] op_sel_hi:[0,1,1]
	v_and_b32_e32 v57, 0xffff0000, v25
	v_lshlrev_b32_e32 v56, 16, v25
	v_pk_fma_f32 v[24:25], v[176:177], v[56:57], v[48:49] op_sel_hi:[0,1,1]
	v_pk_fma_f32 v[154:155], v[178:179], v[24:25], v[78:79] op_sel_hi:[0,1,1] neg_lo:[0,0,1] neg_hi:[0,0,1]
	v_pk_fma_f32 v[24:25], v[160:161], v[54:55], v[156:157] op_sel_hi:[0,1,1]
	v_pk_fma_f32 v[24:25], v[162:163], v[74:75], v[24:25] op_sel_hi:[0,1,1]
	v_pk_fma_f32 v[24:25], v[164:165], v[58:59], v[24:25] op_sel_hi:[0,1,1]
	v_pk_fma_f32 v[24:25], v[166:167], v[106:107], v[24:25] op_sel_hi:[0,1,1]
	v_pk_fma_f32 v[24:25], v[168:169], v[108:109], v[24:25] op_sel_hi:[0,1,1]
	v_pk_fma_f32 v[24:25], v[170:171], v[110:111], v[24:25] op_sel_hi:[0,1,1]
	v_pk_fma_f32 v[24:25], v[172:173], v[46:47], v[24:25] op_sel_hi:[0,1,1]
	v_pk_fma_f32 v[24:25], v[174:175], v[42:43], v[24:25] op_sel_hi:[0,1,1]
	v_and_b32_e32 v49, 0xffff0000, v26
	v_lshlrev_b32_e32 v48, 16, v26
	v_pk_fma_f32 v[24:25], v[176:177], v[48:49], v[24:25] op_sel_hi:[0,1,1]
	v_pk_fma_f32 v[156:157], v[178:179], v[24:25], v[74:75] op_sel_hi:[0,1,1] neg_lo:[0,0,1] neg_hi:[0,0,1]
	v_pk_fma_f32 v[24:25], v[160:161], v[114:115], v[158:159] op_sel_hi:[0,1,1]
	v_pk_fma_f32 v[24:25], v[162:163], v[70:71], v[24:25] op_sel_hi:[0,1,1]
	v_pk_fma_f32 v[24:25], v[164:165], v[116:117], v[24:25] op_sel_hi:[0,1,1]
	v_pk_fma_f32 v[24:25], v[166:167], v[44:45], v[24:25] op_sel_hi:[0,1,1]
	v_pk_fma_f32 v[24:25], v[168:169], v[118:119], v[24:25] op_sel_hi:[0,1,1]
	v_pk_fma_f32 v[24:25], v[170:171], v[52:53], v[24:25] op_sel_hi:[0,1,1]
	s_or_b32 s42, s44, 1
	v_pk_fma_f32 v[24:25], v[172:173], v[40:41], v[24:25] op_sel_hi:[0,1,1]
	s_ashr_i32 s43, s42, 31
	v_pk_fma_f32 v[158:159], v[174:175], v[30:31], v[24:25] op_sel_hi:[0,1,1]
	v_and_b32_e32 v25, 0xffff0000, v27
	v_lshlrev_b32_e32 v24, 16, v27
	s_lshl_b64 s[42:43], s[42:43], 11
	v_pk_fma_f32 v[26:27], v[176:177], v[24:25], v[158:159] op_sel_hi:[0,1,1]
	s_add_u32 s42, s52, s42
	v_pk_fma_f32 v[26:27], v[178:179], v[26:27], v[70:71] op_sel_hi:[0,1,1] neg_lo:[0,0,1] neg_hi:[0,0,1]
	s_addc_u32 s43, s53, s43
	v_cvt_pk_bf16_f32 v152, v152, v153
	v_cvt_pk_bf16_f32 v153, v154, v155
	v_cvt_pk_bf16_f32 v154, v156, v157
	v_cvt_pk_bf16_f32 v155, v26, v27
	v_lshl_add_u64 v[26:27], s[42:43], 0, v[34:35]
	global_store_dwordx4 v[26:27], v[152:155], off offset:512
	v_sub_u32_e32 v26, s35, v32
	v_add_u32_e32 v27, s35, v32
	v_max_i32_e32 v37, 0, v26
	v_min_i32_e32 v153, 0x800, v27
	v_cmp_ge_i32_e32 vcc, s49, v37
	v_cmp_lt_i32_e64 s[42:43], s49, v153
	s_and_b64 s[42:43], vcc, s[42:43]
	v_cmp_ge_i32_e32 vcc, s48, v37
	v_cndmask_b32_e64 v26, 0, 1.0, s[42:43]
	v_cmp_lt_i32_e64 s[42:43], s48, v153
	s_and_b64 s[42:43], vcc, s[42:43]
	v_cmp_ge_i32_e32 vcc, s31, v37
	v_cndmask_b32_e64 v152, 0, 1.0, s[42:43]
	v_cmp_lt_i32_e64 s[42:43], s31, v153
	s_and_b64 s[42:43], vcc, s[42:43]
	v_cmp_ge_i32_e32 vcc, s30, v37
	v_cndmask_b32_e64 v154, 0, 1.0, s[42:43]
	v_cmp_lt_i32_e64 s[42:43], s30, v153
	s_and_b64 s[42:43], vcc, s[42:43]
	v_cmp_ge_i32_e32 vcc, s47, v37
	v_cndmask_b32_e64 v156, 0, 1.0, s[42:43]
	v_cmp_lt_i32_e64 s[42:43], s47, v153
	s_and_b64 s[42:43], vcc, s[42:43]
	v_pk_fma_f32 v[132:133], v[26:27], v[132:133], 0 op_sel_hi:[0,1,0]
	v_cndmask_b32_e64 v158, 0, 1.0, s[42:43]
	v_cmp_gt_i32_e32 vcc, s39, v37
	v_cmp_le_i32_e64 s[42:43], s39, v153
	v_pk_fma_f32 v[132:133], v[152:153], v[142:143], v[132:133] op_sel_hi:[0,1,1]
	s_and_b64 s[42:43], vcc, s[42:43]
	v_pk_fma_f32 v[132:133], v[154:155], v[134:135], v[132:133] op_sel_hi:[0,1,1]
	v_cndmask_b32_e64 v160, 0, 1.0, s[42:43]
	v_cmp_ge_i32_e32 vcc, s39, v37
	v_cmp_lt_i32_e64 s[42:43], s39, v153
	v_pk_fma_f32 v[132:133], v[156:157], v[122:123], v[132:133] op_sel_hi:[0,1,1]
	s_and_b64 s[42:43], vcc, s[42:43]
	v_pk_fma_f32 v[132:133], v[158:159], v[100:101], v[132:133] op_sel_hi:[0,1,1]
	v_cndmask_b32_e64 v162, 0, 1.0, s[42:43]
	v_pk_fma_f32 v[132:133], v[160:161], v[66:67], v[132:133] op_sel_hi:[0,1,1]
	v_cmp_ge_i32_e32 vcc, s34, v37
	v_cmp_lt_i32_e64 s[42:43], s34, v153
	v_pk_fma_f32 v[130:131], v[26:27], v[130:131], 0 op_sel_hi:[0,1,0]
	v_pk_fma_f32 v[164:165], v[162:163], v[92:93], v[132:133] op_sel_hi:[0,1,1]
	v_pk_fma_f32 v[132:133], v[26:27], v[148:149], 0 op_sel_hi:[0,1,0]
	v_pk_fma_f32 v[26:27], v[26:27], v[150:151], 0 op_sel_hi:[0,1,0]
	s_and_b64 s[42:43], vcc, s[42:43]
	v_pk_fma_f32 v[130:131], v[152:153], v[140:141], v[130:131] op_sel_hi:[0,1,1]
	v_pk_fma_f32 v[132:133], v[152:153], v[144:145], v[132:133] op_sel_hi:[0,1,1]
	v_pk_fma_f32 v[26:27], v[152:153], v[146:147], v[26:27] op_sel_hi:[0,1,1]
	v_cndmask_b32_e64 v152, 0, 1.0, s[42:43]
	v_cmp_ge_i32_e32 vcc, s35, v37
	v_cmp_lt_i32_e64 s[42:43], s35, v153
	s_and_b64 s[42:43], vcc, s[42:43]
	v_pk_fma_f32 v[130:131], v[154:155], v[128:129], v[130:131] op_sel_hi:[0,1,1]
	v_pk_fma_f32 v[132:133], v[154:155], v[136:137], v[132:133] op_sel_hi:[0,1,1]
	v_pk_fma_f32 v[26:27], v[154:155], v[138:139], v[26:27] op_sel_hi:[0,1,1]
	v_cndmask_b32_e64 v154, 0, 1.0, s[42:43]
	v_cmp_ge_i32_e32 vcc, s40, v37
	v_cmp_lt_i32_e64 s[42:43], s40, v153
	s_and_b64 s[42:43], vcc, s[42:43]
	v_pk_fma_f32 v[130:131], v[156:157], v[120:121], v[130:131] op_sel_hi:[0,1,1]
	v_pk_fma_f32 v[132:133], v[156:157], v[124:125], v[132:133] op_sel_hi:[0,1,1]
	v_pk_fma_f32 v[26:27], v[156:157], v[126:127], v[26:27] op_sel_hi:[0,1,1]
	v_cndmask_b32_e64 v156, 0, 1.0, s[42:43]
	v_cmp_ge_i32_e32 vcc, s41, v37
	v_cmp_lt_i32_e64 s[42:43], s41, v153
	s_and_b64 s[42:43], vcc, s[42:43]
	v_pk_fma_f32 v[130:131], v[158:159], v[98:99], v[130:131] op_sel_hi:[0,1,1]
	v_pk_fma_f32 v[132:133], v[158:159], v[104:105], v[132:133] op_sel_hi:[0,1,1]
	v_pk_fma_f32 v[26:27], v[158:159], v[112:113], v[26:27] op_sel_hi:[0,1,1]
	v_cndmask_b32_e64 v158, 0, 1.0, s[42:43]
	v_cmp_ge_i32_e32 vcc, s46, v37
	v_cmp_lt_i32_e64 s[42:43], s46, v153
	s_and_b64 s[42:43], vcc, s[42:43]
	v_pk_fma_f32 v[130:131], v[160:161], v[68:69], v[130:131] op_sel_hi:[0,1,1]
	v_pk_fma_f32 v[132:133], v[160:161], v[64:65], v[132:133] op_sel_hi:[0,1,1]
	v_pk_fma_f32 v[26:27], v[160:161], v[62:63], v[26:27] op_sel_hi:[0,1,1]
	v_cndmask_b32_e64 v160, 0, 1.0, s[42:43]
	v_cmp_ge_i32_e32 vcc, s26, v37
	v_cmp_lt_i32_e64 s[42:43], s26, v153
	v_pk_fma_f32 v[150:151], v[162:163], v[114:115], v[26:27] op_sel_hi:[0,1,1]
	s_and_b64 s[42:43], vcc, s[42:43]
	v_sub_u32_e32 v26, v153, v37
	v_pk_fma_f32 v[130:131], v[162:163], v[82:83], v[130:131] op_sel_hi:[0,1,1]
	v_pk_fma_f32 v[148:149], v[162:163], v[54:55], v[132:133] op_sel_hi:[0,1,1]
	v_cndmask_b32_e64 v162, 0, 1.0, s[42:43]
	v_cmp_ge_i32_e32 vcc, s27, v37
	v_cmp_lt_i32_e64 s[42:43], s27, v153
	v_cvt_f32_i32_e32 v26, v26
	s_and_b64 s[42:43], vcc, s[42:43]
	v_cndmask_b32_e64 v166, 0, 1.0, s[42:43]
	v_cmp_ge_i32_e32 vcc, s45, v37
	v_cmp_lt_i32_e64 s[42:43], s45, v153
	s_and_b64 s[42:43], vcc, s[42:43]
	s_add_i32 s49, s39, 9
	v_cndmask_b32_e64 v168, 0, 1.0, s[42:43]
	v_div_scale_f32 v27, s[42:43], v26, v26, 1.0
	v_cmp_ge_i32_e32 vcc, s49, v37
	v_rcp_f32_e32 v37, v27
	v_cmp_lt_i32_e64 s[42:43], s49, v153
	s_and_b64 s[42:43], vcc, s[42:43]
	global_load_dwordx4 v[0:3], v[0:1], off offset:1536
	v_fma_f32 v132, -v27, v37, 1.0
	v_fmac_f32_e32 v37, v132, v37
	v_div_scale_f32 v132, vcc, 1.0, v26, 1.0
	v_mul_f32_e32 v133, v132, v37
	v_fma_f32 v153, -v27, v133, v132
	v_fmac_f32_e32 v133, v153, v37
	v_fma_f32 v27, -v27, v133, v132
	v_div_fmas_f32 v27, v27, v37, v133
	v_div_fixup_f32 v172, v27, v26, 1.0
	v_pk_fma_f32 v[26:27], v[152:153], v[80:81], v[130:131] op_sel_hi:[0,1,1]
	v_pk_fma_f32 v[26:27], v[154:155], v[84:85], v[26:27] op_sel_hi:[0,1,1]
	v_pk_fma_f32 v[26:27], v[156:157], v[86:87], v[26:27] op_sel_hi:[0,1,1]
	v_pk_fma_f32 v[26:27], v[158:159], v[88:89], v[26:27] op_sel_hi:[0,1,1]
	v_pk_fma_f32 v[26:27], v[160:161], v[90:91], v[26:27] op_sel_hi:[0,1,1]
	v_pk_fma_f32 v[26:27], v[162:163], v[76:77], v[26:27] op_sel_hi:[0,1,1]
	v_pk_fma_f32 v[26:27], v[166:167], v[72:73], v[26:27] op_sel_hi:[0,1,1]
	v_cndmask_b32_e64 v170, 0, 1.0, s[42:43]
	v_pk_fma_f32 v[26:27], v[168:169], v[60:61], v[26:27] op_sel_hi:[0,1,1]
	s_waitcnt vmcnt(7)
	v_and_b32_e32 v133, 0xffff0000, v20
	v_lshlrev_b32_e32 v132, 16, v20
	v_pk_fma_f32 v[26:27], v[170:171], v[132:133], v[26:27] op_sel_hi:[0,1,1]
	v_pk_fma_f32 v[174:175], v[172:173], v[26:27], v[84:85] op_sel_hi:[0,1,1] neg_lo:[0,0,1] neg_hi:[0,0,1]
	v_pk_fma_f32 v[26:27], v[152:153], v[78:79], v[164:165] op_sel_hi:[0,1,1]
	v_pk_fma_f32 v[26:27], v[154:155], v[94:95], v[26:27] op_sel_hi:[0,1,1]
	v_pk_fma_f32 v[26:27], v[156:157], v[96:97], v[26:27] op_sel_hi:[0,1,1]
	v_pk_fma_f32 v[26:27], v[158:159], v[102:103], v[26:27] op_sel_hi:[0,1,1]
	v_pk_fma_f32 v[26:27], v[160:161], v[50:51], v[26:27] op_sel_hi:[0,1,1]
	v_pk_fma_f32 v[26:27], v[162:163], v[38:39], v[26:27] op_sel_hi:[0,1,1]
	v_pk_fma_f32 v[26:27], v[166:167], v[28:29], v[26:27] op_sel_hi:[0,1,1]
	v_pk_fma_f32 v[26:27], v[168:169], v[56:57], v[26:27] op_sel_hi:[0,1,1]
	v_and_b32_e32 v131, 0xffff0000, v21
	v_lshlrev_b32_e32 v130, 16, v21
	v_pk_fma_f32 v[20:21], v[170:171], v[130:131], v[26:27] op_sel_hi:[0,1,1]
	v_pk_fma_f32 v[164:165], v[172:173], v[20:21], v[94:95] op_sel_hi:[0,1,1] neg_lo:[0,0,1] neg_hi:[0,0,1]
	v_pk_fma_f32 v[20:21], v[152:153], v[74:75], v[148:149] op_sel_hi:[0,1,1]
	v_pk_fma_f32 v[20:21], v[154:155], v[58:59], v[20:21] op_sel_hi:[0,1,1]
	v_pk_fma_f32 v[20:21], v[156:157], v[106:107], v[20:21] op_sel_hi:[0,1,1]
	v_pk_fma_f32 v[20:21], v[158:159], v[108:109], v[20:21] op_sel_hi:[0,1,1]
	v_pk_fma_f32 v[20:21], v[160:161], v[110:111], v[20:21] op_sel_hi:[0,1,1]
	v_pk_fma_f32 v[20:21], v[162:163], v[46:47], v[20:21] op_sel_hi:[0,1,1]
	v_pk_fma_f32 v[20:21], v[166:167], v[42:43], v[20:21] op_sel_hi:[0,1,1]
	v_pk_fma_f32 v[20:21], v[168:169], v[48:49], v[20:21] op_sel_hi:[0,1,1]
	v_and_b32_e32 v27, 0xffff0000, v22
	v_lshlrev_b32_e32 v26, 16, v22
	v_pk_fma_f32 v[20:21], v[170:171], v[26:27], v[20:21] op_sel_hi:[0,1,1]
	v_pk_fma_f32 v[176:177], v[172:173], v[20:21], v[58:59] op_sel_hi:[0,1,1] neg_lo:[0,0,1] neg_hi:[0,0,1]
	v_pk_fma_f32 v[20:21], v[152:153], v[70:71], v[150:151] op_sel_hi:[0,1,1]
	v_pk_fma_f32 v[20:21], v[154:155], v[116:117], v[20:21] op_sel_hi:[0,1,1]
	v_pk_fma_f32 v[20:21], v[156:157], v[44:45], v[20:21] op_sel_hi:[0,1,1]
	v_pk_fma_f32 v[20:21], v[158:159], v[118:119], v[20:21] op_sel_hi:[0,1,1]
	v_pk_fma_f32 v[20:21], v[160:161], v[52:53], v[20:21] op_sel_hi:[0,1,1]
	v_pk_fma_f32 v[20:21], v[162:163], v[40:41], v[20:21] op_sel_hi:[0,1,1]
	s_or_b32 s42, s44, 2
	v_pk_fma_f32 v[20:21], v[166:167], v[30:31], v[20:21] op_sel_hi:[0,1,1]
	s_ashr_i32 s43, s42, 31
	v_pk_fma_f32 v[148:149], v[168:169], v[24:25], v[20:21] op_sel_hi:[0,1,1]
	v_and_b32_e32 v21, 0xffff0000, v23
	v_lshlrev_b32_e32 v20, 16, v23
	s_lshl_b64 s[42:43], s[42:43], 11
	v_pk_fma_f32 v[22:23], v[170:171], v[20:21], v[148:149] op_sel_hi:[0,1,1]
	s_add_u32 s42, s52, s42
	v_pk_fma_f32 v[22:23], v[172:173], v[22:23], v[116:117] op_sel_hi:[0,1,1] neg_lo:[0,0,1] neg_hi:[0,0,1]
	s_addc_u32 s43, s53, s43
	v_cvt_pk_bf16_f32 v148, v174, v175
	v_cvt_pk_bf16_f32 v149, v164, v165
	v_cvt_pk_bf16_f32 v150, v176, v177
	v_cvt_pk_bf16_f32 v151, v22, v23
	v_lshl_add_u64 v[22:23], s[42:43], 0, v[34:35]
	global_store_dwordx4 v[22:23], v[148:151], off offset:512
	v_sub_u32_e32 v22, s40, v32
	v_add_u32_e32 v23, s40, v32
	v_max_i32_e32 v37, 0, v22
	v_min_i32_e32 v149, 0x800, v23
	v_cmp_ge_i32_e32 vcc, s48, v37
	v_cmp_lt_i32_e64 s[42:43], s48, v149
	s_and_b64 s[42:43], vcc, s[42:43]
	v_cmp_ge_i32_e32 vcc, s31, v37
	v_cndmask_b32_e64 v22, 0, 1.0, s[42:43]
	v_cmp_lt_i32_e64 s[42:43], s31, v149
	s_and_b64 s[42:43], vcc, s[42:43]
	v_cmp_ge_i32_e32 vcc, s30, v37
	v_cndmask_b32_e64 v148, 0, 1.0, s[42:43]
	v_cmp_lt_i32_e64 s[42:43], s30, v149
	s_and_b64 s[42:43], vcc, s[42:43]
	v_cmp_ge_i32_e32 vcc, s47, v37
	v_cndmask_b32_e64 v150, 0, 1.0, s[42:43]
	v_cmp_lt_i32_e64 s[42:43], s47, v149
	s_and_b64 s[42:43], vcc, s[42:43]
	v_cmp_gt_i32_e32 vcc, s39, v37
	v_cndmask_b32_e64 v152, 0, 1.0, s[42:43]
	v_cmp_le_i32_e64 s[42:43], s39, v149
	s_and_b64 s[42:43], vcc, s[42:43]
	v_pk_fma_f32 v[142:143], v[22:23], v[142:143], 0 op_sel_hi:[0,1,0]
	v_cndmask_b32_e64 v154, 0, 1.0, s[42:43]
	v_cmp_ge_i32_e32 vcc, s39, v37
	v_cmp_lt_i32_e64 s[42:43], s39, v149
	v_pk_fma_f32 v[142:143], v[148:149], v[134:135], v[142:143] op_sel_hi:[0,1,1]
	s_and_b64 s[42:43], vcc, s[42:43]
	v_pk_fma_f32 v[142:143], v[150:151], v[122:123], v[142:143] op_sel_hi:[0,1,1]
	v_cndmask_b32_e64 v156, 0, 1.0, s[42:43]
	v_cmp_ge_i32_e32 vcc, s34, v37
	v_cmp_lt_i32_e64 s[42:43], s34, v149
	v_pk_fma_f32 v[142:143], v[152:153], v[100:101], v[142:143] op_sel_hi:[0,1,1]
	s_and_b64 s[42:43], vcc, s[42:43]
	v_pk_fma_f32 v[142:143], v[154:155], v[66:67], v[142:143] op_sel_hi:[0,1,1]
	v_cndmask_b32_e64 v158, 0, 1.0, s[42:43]
	v_pk_fma_f32 v[142:143], v[156:157], v[92:93], v[142:143] op_sel_hi:[0,1,1]
	v_cmp_ge_i32_e32 vcc, s35, v37
	v_cmp_lt_i32_e64 s[42:43], s35, v149
	v_pk_fma_f32 v[140:141], v[22:23], v[140:141], 0 op_sel_hi:[0,1,0]
	v_pk_fma_f32 v[160:161], v[158:159], v[78:79], v[142:143] op_sel_hi:[0,1,1]
	v_pk_fma_f32 v[142:143], v[22:23], v[144:145], 0 op_sel_hi:[0,1,0]
	v_pk_fma_f32 v[22:23], v[22:23], v[146:147], 0 op_sel_hi:[0,1,0]
	s_and_b64 s[42:43], vcc, s[42:43]
	v_pk_fma_f32 v[140:141], v[148:149], v[128:129], v[140:141] op_sel_hi:[0,1,1]
	v_pk_fma_f32 v[142:143], v[148:149], v[136:137], v[142:143] op_sel_hi:[0,1,1]
	v_pk_fma_f32 v[22:23], v[148:149], v[138:139], v[22:23] op_sel_hi:[0,1,1]
	v_cndmask_b32_e64 v148, 0, 1.0, s[42:43]
	v_cmp_ge_i32_e32 vcc, s40, v37
	v_cmp_lt_i32_e64 s[42:43], s40, v149
	s_and_b64 s[42:43], vcc, s[42:43]
	v_pk_fma_f32 v[140:141], v[150:151], v[120:121], v[140:141] op_sel_hi:[0,1,1]
	v_pk_fma_f32 v[142:143], v[150:151], v[124:125], v[142:143] op_sel_hi:[0,1,1]
	v_pk_fma_f32 v[22:23], v[150:151], v[126:127], v[22:23] op_sel_hi:[0,1,1]
	v_cndmask_b32_e64 v150, 0, 1.0, s[42:43]
	v_cmp_ge_i32_e32 vcc, s41, v37
	v_cmp_lt_i32_e64 s[42:43], s41, v149
	s_and_b64 s[42:43], vcc, s[42:43]
	v_pk_fma_f32 v[140:141], v[152:153], v[98:99], v[140:141] op_sel_hi:[0,1,1]
	v_pk_fma_f32 v[142:143], v[152:153], v[104:105], v[142:143] op_sel_hi:[0,1,1]
	v_pk_fma_f32 v[22:23], v[152:153], v[112:113], v[22:23] op_sel_hi:[0,1,1]
	v_cndmask_b32_e64 v152, 0, 1.0, s[42:43]
	v_cmp_ge_i32_e32 vcc, s46, v37
	v_cmp_lt_i32_e64 s[42:43], s46, v149
	s_and_b64 s[42:43], vcc, s[42:43]
	v_pk_fma_f32 v[140:141], v[154:155], v[68:69], v[140:141] op_sel_hi:[0,1,1]
	v_pk_fma_f32 v[142:143], v[154:155], v[64:65], v[142:143] op_sel_hi:[0,1,1]
	v_pk_fma_f32 v[22:23], v[154:155], v[62:63], v[22:23] op_sel_hi:[0,1,1]
	v_cndmask_b32_e64 v154, 0, 1.0, s[42:43]
	v_cmp_ge_i32_e32 vcc, s26, v37
	v_cmp_lt_i32_e64 s[42:43], s26, v149
	s_and_b64 s[42:43], vcc, s[42:43]
	v_pk_fma_f32 v[140:141], v[156:157], v[82:83], v[140:141] op_sel_hi:[0,1,1]
	v_pk_fma_f32 v[142:143], v[156:157], v[54:55], v[142:143] op_sel_hi:[0,1,1]
	v_pk_fma_f32 v[22:23], v[156:157], v[114:115], v[22:23] op_sel_hi:[0,1,1]
	v_cndmask_b32_e64 v156, 0, 1.0, s[42:43]
	v_cmp_ge_i32_e32 vcc, s27, v37
	v_cmp_lt_i32_e64 s[42:43], s27, v149
	v_pk_fma_f32 v[146:147], v[158:159], v[70:71], v[22:23] op_sel_hi:[0,1,1]
	s_and_b64 s[42:43], vcc, s[42:43]
	v_sub_u32_e32 v22, v149, v37
	v_pk_fma_f32 v[140:141], v[158:159], v[80:81], v[140:141] op_sel_hi:[0,1,1]
	v_pk_fma_f32 v[144:145], v[158:159], v[74:75], v[142:143] op_sel_hi:[0,1,1]
	v_cndmask_b32_e64 v158, 0, 1.0, s[42:43]
	v_cmp_ge_i32_e32 vcc, s45, v37
	v_cmp_lt_i32_e64 s[42:43], s45, v149
	v_cvt_f32_i32_e32 v22, v22
	s_and_b64 s[42:43], vcc, s[42:43]
	v_cndmask_b32_e64 v162, 0, 1.0, s[42:43]
	v_cmp_ge_i32_e32 vcc, s49, v37
	v_cmp_lt_i32_e64 s[42:43], s49, v149
	s_and_b64 s[42:43], vcc, s[42:43]
	s_add_i32 s48, s39, 10
	v_cndmask_b32_e64 v164, 0, 1.0, s[42:43]
	v_div_scale_f32 v23, s[42:43], v22, v22, 1.0
	v_cmp_ge_i32_e32 vcc, s48, v37
	v_rcp_f32_e32 v37, v23
	v_cmp_lt_i32_e64 s[42:43], s48, v149
	s_and_b64 s[42:43], vcc, s[42:43]
	v_fma_f32 v142, -v23, v37, 1.0
	v_fmac_f32_e32 v37, v142, v37
	v_div_scale_f32 v142, vcc, 1.0, v22, 1.0
	v_mul_f32_e32 v143, v142, v37
	v_fma_f32 v149, -v23, v143, v142
	v_fmac_f32_e32 v143, v149, v37
	v_fma_f32 v23, -v23, v143, v142
	v_div_fmas_f32 v23, v23, v37, v143
	v_div_fixup_f32 v168, v23, v22, 1.0
	v_pk_fma_f32 v[22:23], v[148:149], v[84:85], v[140:141] op_sel_hi:[0,1,1]
	v_pk_fma_f32 v[22:23], v[150:151], v[86:87], v[22:23] op_sel_hi:[0,1,1]
	v_pk_fma_f32 v[22:23], v[152:153], v[88:89], v[22:23] op_sel_hi:[0,1,1]
	v_pk_fma_f32 v[22:23], v[154:155], v[90:91], v[22:23] op_sel_hi:[0,1,1]
	v_pk_fma_f32 v[22:23], v[156:157], v[76:77], v[22:23] op_sel_hi:[0,1,1]
	v_pk_fma_f32 v[22:23], v[158:159], v[72:73], v[22:23] op_sel_hi:[0,1,1]
	v_pk_fma_f32 v[22:23], v[162:163], v[60:61], v[22:23] op_sel_hi:[0,1,1]
	v_cndmask_b32_e64 v166, 0, 1.0, s[42:43]
	v_pk_fma_f32 v[22:23], v[164:165], v[132:133], v[22:23] op_sel_hi:[0,1,1]
	s_waitcnt vmcnt(7)
	v_and_b32_e32 v143, 0xffff0000, v16
	v_lshlrev_b32_e32 v142, 16, v16
	v_pk_fma_f32 v[22:23], v[166:167], v[142:143], v[22:23] op_sel_hi:[0,1,1]
	v_pk_fma_f32 v[170:171], v[168:169], v[22:23], v[86:87] op_sel_hi:[0,1,1] neg_lo:[0,0,1] neg_hi:[0,0,1]
	v_pk_fma_f32 v[22:23], v[148:149], v[94:95], v[160:161] op_sel_hi:[0,1,1]
	v_pk_fma_f32 v[22:23], v[150:151], v[96:97], v[22:23] op_sel_hi:[0,1,1]
	v_pk_fma_f32 v[22:23], v[152:153], v[102:103], v[22:23] op_sel_hi:[0,1,1]
	v_pk_fma_f32 v[22:23], v[154:155], v[50:51], v[22:23] op_sel_hi:[0,1,1]
	v_pk_fma_f32 v[22:23], v[156:157], v[38:39], v[22:23] op_sel_hi:[0,1,1]
	v_pk_fma_f32 v[22:23], v[158:159], v[28:29], v[22:23] op_sel_hi:[0,1,1]
	v_pk_fma_f32 v[22:23], v[162:163], v[56:57], v[22:23] op_sel_hi:[0,1,1]
	v_pk_fma_f32 v[22:23], v[164:165], v[130:131], v[22:23] op_sel_hi:[0,1,1]
	v_and_b32_e32 v141, 0xffff0000, v17
	v_lshlrev_b32_e32 v140, 16, v17
	v_pk_fma_f32 v[16:17], v[166:167], v[140:141], v[22:23] op_sel_hi:[0,1,1]
	v_pk_fma_f32 v[160:161], v[168:169], v[16:17], v[96:97] op_sel_hi:[0,1,1] neg_lo:[0,0,1] neg_hi:[0,0,1]
	v_pk_fma_f32 v[16:17], v[148:149], v[58:59], v[144:145] op_sel_hi:[0,1,1]
	v_pk_fma_f32 v[16:17], v[150:151], v[106:107], v[16:17] op_sel_hi:[0,1,1]
	v_pk_fma_f32 v[16:17], v[152:153], v[108:109], v[16:17] op_sel_hi:[0,1,1]
	v_pk_fma_f32 v[16:17], v[154:155], v[110:111], v[16:17] op_sel_hi:[0,1,1]
	v_pk_fma_f32 v[16:17], v[156:157], v[46:47], v[16:17] op_sel_hi:[0,1,1]
	v_pk_fma_f32 v[16:17], v[158:159], v[42:43], v[16:17] op_sel_hi:[0,1,1]
	v_pk_fma_f32 v[16:17], v[162:163], v[48:49], v[16:17] op_sel_hi:[0,1,1]
	v_pk_fma_f32 v[16:17], v[164:165], v[26:27], v[16:17] op_sel_hi:[0,1,1]
	v_and_b32_e32 v23, 0xffff0000, v18
	v_lshlrev_b32_e32 v22, 16, v18
	v_pk_fma_f32 v[16:17], v[166:167], v[22:23], v[16:17] op_sel_hi:[0,1,1]
	v_pk_fma_f32 v[172:173], v[168:169], v[16:17], v[106:107] op_sel_hi:[0,1,1] neg_lo:[0,0,1] neg_hi:[0,0,1]
	v_pk_fma_f32 v[16:17], v[148:149], v[116:117], v[146:147] op_sel_hi:[0,1,1]
	v_pk_fma_f32 v[16:17], v[150:151], v[44:45], v[16:17] op_sel_hi:[0,1,1]
	v_pk_fma_f32 v[16:17], v[152:153], v[118:119], v[16:17] op_sel_hi:[0,1,1]
	v_pk_fma_f32 v[16:17], v[154:155], v[52:53], v[16:17] op_sel_hi:[0,1,1]
	v_pk_fma_f32 v[16:17], v[156:157], v[40:41], v[16:17] op_sel_hi:[0,1,1]
	v_pk_fma_f32 v[16:17], v[158:159], v[30:31], v[16:17] op_sel_hi:[0,1,1]
	s_or_b32 s42, s44, 3
	v_pk_fma_f32 v[16:17], v[162:163], v[24:25], v[16:17] op_sel_hi:[0,1,1]
	s_ashr_i32 s43, s42, 31
	v_pk_fma_f32 v[144:145], v[164:165], v[20:21], v[16:17] op_sel_hi:[0,1,1]
	v_and_b32_e32 v17, 0xffff0000, v19
	v_lshlrev_b32_e32 v16, 16, v19
	s_lshl_b64 s[42:43], s[42:43], 11
	v_pk_fma_f32 v[18:19], v[166:167], v[16:17], v[144:145] op_sel_hi:[0,1,1]
	s_add_u32 s42, s52, s42
	v_pk_fma_f32 v[18:19], v[168:169], v[18:19], v[44:45] op_sel_hi:[0,1,1] neg_lo:[0,0,1] neg_hi:[0,0,1]
	s_addc_u32 s43, s53, s43
	v_cvt_pk_bf16_f32 v144, v170, v171
	v_cvt_pk_bf16_f32 v145, v160, v161
	v_cvt_pk_bf16_f32 v146, v172, v173
	v_cvt_pk_bf16_f32 v147, v18, v19
	v_lshl_add_u64 v[18:19], s[42:43], 0, v[34:35]
	global_store_dwordx4 v[18:19], v[144:147], off offset:512
	v_sub_u32_e32 v18, s41, v32
	v_add_u32_e32 v19, s41, v32
	v_max_i32_e32 v37, 0, v18
	v_min_i32_e32 v145, 0x800, v19
	v_cmp_ge_i32_e32 vcc, s31, v37
	v_cmp_lt_i32_e64 s[42:43], s31, v145
	s_and_b64 s[42:43], vcc, s[42:43]
	v_cmp_ge_i32_e32 vcc, s30, v37
	v_cndmask_b32_e64 v18, 0, 1.0, s[42:43]
	v_cmp_lt_i32_e64 s[42:43], s30, v145
	s_and_b64 s[42:43], vcc, s[42:43]
	v_cmp_ge_i32_e32 vcc, s47, v37
	v_cndmask_b32_e64 v144, 0, 1.0, s[42:43]
	v_cmp_lt_i32_e64 s[42:43], s47, v145
	s_and_b64 s[42:43], vcc, s[42:43]
	v_cmp_gt_i32_e32 vcc, s39, v37
	v_cndmask_b32_e64 v146, 0, 1.0, s[42:43]
	v_cmp_le_i32_e64 s[42:43], s39, v145
	s_and_b64 s[42:43], vcc, s[42:43]
	v_cmp_ge_i32_e32 vcc, s39, v37
	v_cndmask_b32_e64 v148, 0, 1.0, s[42:43]
	v_cmp_lt_i32_e64 s[42:43], s39, v145
	s_and_b64 s[42:43], vcc, s[42:43]
	v_pk_fma_f32 v[134:135], v[18:19], v[134:135], 0 op_sel_hi:[0,1,0]
	v_cndmask_b32_e64 v150, 0, 1.0, s[42:43]
	v_cmp_ge_i32_e32 vcc, s34, v37
	v_cmp_lt_i32_e64 s[42:43], s34, v145
	v_pk_fma_f32 v[134:135], v[144:145], v[122:123], v[134:135] op_sel_hi:[0,1,1]
	s_and_b64 s[42:43], vcc, s[42:43]
	v_pk_fma_f32 v[134:135], v[146:147], v[100:101], v[134:135] op_sel_hi:[0,1,1]
	v_cndmask_b32_e64 v152, 0, 1.0, s[42:43]
	v_cmp_ge_i32_e32 vcc, s35, v37
	v_cmp_lt_i32_e64 s[42:43], s35, v145
	v_pk_fma_f32 v[134:135], v[148:149], v[66:67], v[134:135] op_sel_hi:[0,1,1]
	s_and_b64 s[42:43], vcc, s[42:43]
	v_pk_fma_f32 v[134:135], v[150:151], v[92:93], v[134:135] op_sel_hi:[0,1,1]
	v_cndmask_b32_e64 v154, 0, 1.0, s[42:43]
	v_pk_fma_f32 v[134:135], v[152:153], v[78:79], v[134:135] op_sel_hi:[0,1,1]
	v_cmp_ge_i32_e32 vcc, s40, v37
	v_cmp_lt_i32_e64 s[42:43], s40, v145
	v_pk_fma_f32 v[128:129], v[18:19], v[128:129], 0 op_sel_hi:[0,1,0]
	v_pk_fma_f32 v[156:157], v[154:155], v[94:95], v[134:135] op_sel_hi:[0,1,1]
	v_pk_fma_f32 v[134:135], v[18:19], v[136:137], 0 op_sel_hi:[0,1,0]
	v_pk_fma_f32 v[18:19], v[18:19], v[138:139], 0 op_sel_hi:[0,1,0]
	s_and_b64 s[42:43], vcc, s[42:43]
	v_pk_fma_f32 v[128:129], v[144:145], v[120:121], v[128:129] op_sel_hi:[0,1,1]
	v_pk_fma_f32 v[134:135], v[144:145], v[124:125], v[134:135] op_sel_hi:[0,1,1]
	v_pk_fma_f32 v[18:19], v[144:145], v[126:127], v[18:19] op_sel_hi:[0,1,1]
	v_cndmask_b32_e64 v144, 0, 1.0, s[42:43]
	v_cmp_ge_i32_e32 vcc, s41, v37
	v_cmp_lt_i32_e64 s[42:43], s41, v145
	s_and_b64 s[42:43], vcc, s[42:43]
	v_pk_fma_f32 v[128:129], v[146:147], v[98:99], v[128:129] op_sel_hi:[0,1,1]
	v_pk_fma_f32 v[134:135], v[146:147], v[104:105], v[134:135] op_sel_hi:[0,1,1]
	v_pk_fma_f32 v[18:19], v[146:147], v[112:113], v[18:19] op_sel_hi:[0,1,1]
	v_cndmask_b32_e64 v146, 0, 1.0, s[42:43]
	v_cmp_ge_i32_e32 vcc, s46, v37
	v_cmp_lt_i32_e64 s[42:43], s46, v145
	s_and_b64 s[42:43], vcc, s[42:43]
	v_pk_fma_f32 v[128:129], v[148:149], v[68:69], v[128:129] op_sel_hi:[0,1,1]
	v_pk_fma_f32 v[134:135], v[148:149], v[64:65], v[134:135] op_sel_hi:[0,1,1]
	v_pk_fma_f32 v[18:19], v[148:149], v[62:63], v[18:19] op_sel_hi:[0,1,1]
	v_cndmask_b32_e64 v148, 0, 1.0, s[42:43]
	v_cmp_ge_i32_e32 vcc, s26, v37
	v_cmp_lt_i32_e64 s[42:43], s26, v145
	s_and_b64 s[42:43], vcc, s[42:43]
	v_pk_fma_f32 v[128:129], v[150:151], v[82:83], v[128:129] op_sel_hi:[0,1,1]
	v_pk_fma_f32 v[134:135], v[150:151], v[54:55], v[134:135] op_sel_hi:[0,1,1]
	v_pk_fma_f32 v[18:19], v[150:151], v[114:115], v[18:19] op_sel_hi:[0,1,1]
	v_cndmask_b32_e64 v150, 0, 1.0, s[42:43]
	v_cmp_ge_i32_e32 vcc, s27, v37
	v_cmp_lt_i32_e64 s[42:43], s27, v145
	s_and_b64 s[42:43], vcc, s[42:43]
	v_pk_fma_f32 v[128:129], v[152:153], v[80:81], v[128:129] op_sel_hi:[0,1,1]
	v_pk_fma_f32 v[134:135], v[152:153], v[74:75], v[134:135] op_sel_hi:[0,1,1]
	v_pk_fma_f32 v[18:19], v[152:153], v[70:71], v[18:19] op_sel_hi:[0,1,1]
	v_cndmask_b32_e64 v152, 0, 1.0, s[42:43]
	v_cmp_ge_i32_e32 vcc, s45, v37
	v_cmp_lt_i32_e64 s[42:43], s45, v145
	v_pk_fma_f32 v[138:139], v[154:155], v[116:117], v[18:19] op_sel_hi:[0,1,1]
	s_and_b64 s[42:43], vcc, s[42:43]
	v_sub_u32_e32 v18, v145, v37
	v_pk_fma_f32 v[128:129], v[154:155], v[84:85], v[128:129] op_sel_hi:[0,1,1]
	v_pk_fma_f32 v[136:137], v[154:155], v[58:59], v[134:135] op_sel_hi:[0,1,1]
	v_cndmask_b32_e64 v154, 0, 1.0, s[42:43]
	v_cmp_ge_i32_e32 vcc, s49, v37
	v_cmp_lt_i32_e64 s[42:43], s49, v145
	v_cvt_f32_i32_e32 v18, v18
	s_and_b64 s[42:43], vcc, s[42:43]
	v_cndmask_b32_e64 v158, 0, 1.0, s[42:43]
	v_cmp_ge_i32_e32 vcc, s48, v37
	v_cmp_lt_i32_e64 s[42:43], s48, v145
	s_and_b64 s[42:43], vcc, s[42:43]
	s_add_i32 s31, s39, 11
	v_cndmask_b32_e64 v160, 0, 1.0, s[42:43]
	v_div_scale_f32 v19, s[42:43], v18, v18, 1.0
	v_cmp_ge_i32_e32 vcc, s31, v37
	v_rcp_f32_e32 v37, v19
	v_cmp_lt_i32_e64 s[42:43], s31, v145
	s_and_b64 s[42:43], vcc, s[42:43]
	v_fma_f32 v134, -v19, v37, 1.0
	v_fmac_f32_e32 v37, v134, v37
	v_div_scale_f32 v134, vcc, 1.0, v18, 1.0
	v_mul_f32_e32 v135, v134, v37
	v_fma_f32 v145, -v19, v135, v134
	v_fmac_f32_e32 v135, v145, v37
	v_fma_f32 v19, -v19, v135, v134
	v_div_fmas_f32 v19, v19, v37, v135
	v_div_fixup_f32 v164, v19, v18, 1.0
	v_pk_fma_f32 v[18:19], v[144:145], v[86:87], v[128:129] op_sel_hi:[0,1,1]
	v_pk_fma_f32 v[18:19], v[146:147], v[88:89], v[18:19] op_sel_hi:[0,1,1]
	v_pk_fma_f32 v[18:19], v[148:149], v[90:91], v[18:19] op_sel_hi:[0,1,1]
	v_pk_fma_f32 v[18:19], v[150:151], v[76:77], v[18:19] op_sel_hi:[0,1,1]
	v_pk_fma_f32 v[18:19], v[152:153], v[72:73], v[18:19] op_sel_hi:[0,1,1]
	v_pk_fma_f32 v[18:19], v[154:155], v[60:61], v[18:19] op_sel_hi:[0,1,1]
	v_pk_fma_f32 v[18:19], v[158:159], v[132:133], v[18:19] op_sel_hi:[0,1,1]
	v_cndmask_b32_e64 v162, 0, 1.0, s[42:43]
	v_pk_fma_f32 v[18:19], v[160:161], v[142:143], v[18:19] op_sel_hi:[0,1,1]
	s_waitcnt vmcnt(7)
	v_and_b32_e32 v135, 0xffff0000, v12
	v_lshlrev_b32_e32 v134, 16, v12
	v_pk_fma_f32 v[18:19], v[162:163], v[134:135], v[18:19] op_sel_hi:[0,1,1]
	v_pk_fma_f32 v[166:167], v[164:165], v[18:19], v[88:89] op_sel_hi:[0,1,1] neg_lo:[0,0,1] neg_hi:[0,0,1]
	v_pk_fma_f32 v[18:19], v[144:145], v[96:97], v[156:157] op_sel_hi:[0,1,1]
	v_pk_fma_f32 v[18:19], v[146:147], v[102:103], v[18:19] op_sel_hi:[0,1,1]
	v_pk_fma_f32 v[18:19], v[148:149], v[50:51], v[18:19] op_sel_hi:[0,1,1]
	v_pk_fma_f32 v[18:19], v[150:151], v[38:39], v[18:19] op_sel_hi:[0,1,1]
	v_pk_fma_f32 v[18:19], v[152:153], v[28:29], v[18:19] op_sel_hi:[0,1,1]
	v_pk_fma_f32 v[18:19], v[154:155], v[56:57], v[18:19] op_sel_hi:[0,1,1]
	v_pk_fma_f32 v[18:19], v[158:159], v[130:131], v[18:19] op_sel_hi:[0,1,1]
	v_pk_fma_f32 v[18:19], v[160:161], v[140:141], v[18:19] op_sel_hi:[0,1,1]
	v_and_b32_e32 v129, 0xffff0000, v13
	v_lshlrev_b32_e32 v128, 16, v13
	v_pk_fma_f32 v[12:13], v[162:163], v[128:129], v[18:19] op_sel_hi:[0,1,1]
	v_pk_fma_f32 v[156:157], v[164:165], v[12:13], v[102:103] op_sel_hi:[0,1,1] neg_lo:[0,0,1] neg_hi:[0,0,1]
	v_pk_fma_f32 v[12:13], v[144:145], v[106:107], v[136:137] op_sel_hi:[0,1,1]
	v_pk_fma_f32 v[12:13], v[146:147], v[108:109], v[12:13] op_sel_hi:[0,1,1]
	v_pk_fma_f32 v[12:13], v[148:149], v[110:111], v[12:13] op_sel_hi:[0,1,1]
	v_pk_fma_f32 v[12:13], v[150:151], v[46:47], v[12:13] op_sel_hi:[0,1,1]
	v_pk_fma_f32 v[12:13], v[152:153], v[42:43], v[12:13] op_sel_hi:[0,1,1]
	v_pk_fma_f32 v[12:13], v[154:155], v[48:49], v[12:13] op_sel_hi:[0,1,1]
	v_pk_fma_f32 v[12:13], v[158:159], v[26:27], v[12:13] op_sel_hi:[0,1,1]
	v_pk_fma_f32 v[12:13], v[160:161], v[22:23], v[12:13] op_sel_hi:[0,1,1]
	v_and_b32_e32 v19, 0xffff0000, v14
	v_lshlrev_b32_e32 v18, 16, v14
	v_pk_fma_f32 v[12:13], v[162:163], v[18:19], v[12:13] op_sel_hi:[0,1,1]
	v_pk_fma_f32 v[168:169], v[164:165], v[12:13], v[108:109] op_sel_hi:[0,1,1] neg_lo:[0,0,1] neg_hi:[0,0,1]
	v_pk_fma_f32 v[12:13], v[144:145], v[44:45], v[138:139] op_sel_hi:[0,1,1]
	v_pk_fma_f32 v[12:13], v[146:147], v[118:119], v[12:13] op_sel_hi:[0,1,1]
	v_pk_fma_f32 v[12:13], v[148:149], v[52:53], v[12:13] op_sel_hi:[0,1,1]
	v_pk_fma_f32 v[12:13], v[150:151], v[40:41], v[12:13] op_sel_hi:[0,1,1]
	v_pk_fma_f32 v[12:13], v[152:153], v[30:31], v[12:13] op_sel_hi:[0,1,1]
	v_pk_fma_f32 v[12:13], v[154:155], v[24:25], v[12:13] op_sel_hi:[0,1,1]
	s_or_b32 s42, s44, 4
	v_pk_fma_f32 v[12:13], v[158:159], v[20:21], v[12:13] op_sel_hi:[0,1,1]
	s_ashr_i32 s43, s42, 31
	v_pk_fma_f32 v[136:137], v[160:161], v[16:17], v[12:13] op_sel_hi:[0,1,1]
	v_and_b32_e32 v13, 0xffff0000, v15
	v_lshlrev_b32_e32 v12, 16, v15
	s_lshl_b64 s[42:43], s[42:43], 11
	v_pk_fma_f32 v[14:15], v[162:163], v[12:13], v[136:137] op_sel_hi:[0,1,1]
	s_add_u32 s42, s52, s42
	v_pk_fma_f32 v[14:15], v[164:165], v[14:15], v[118:119] op_sel_hi:[0,1,1] neg_lo:[0,0,1] neg_hi:[0,0,1]
	s_addc_u32 s43, s53, s43
	v_cvt_pk_bf16_f32 v136, v166, v167
	v_cvt_pk_bf16_f32 v137, v156, v157
	v_cvt_pk_bf16_f32 v138, v168, v169
	v_cvt_pk_bf16_f32 v139, v14, v15
	v_lshl_add_u64 v[14:15], s[42:43], 0, v[34:35]
	global_store_dwordx4 v[14:15], v[136:139], off offset:512
	v_sub_u32_e32 v14, s46, v32
	v_add_u32_e32 v15, s46, v32
	v_max_i32_e32 v37, 0, v14
	v_min_i32_e32 v137, 0x800, v15
	v_cmp_ge_i32_e32 vcc, s30, v37
	v_cmp_lt_i32_e64 s[42:43], s30, v137
	s_and_b64 s[42:43], vcc, s[42:43]
	v_cmp_ge_i32_e32 vcc, s47, v37
	v_cndmask_b32_e64 v14, 0, 1.0, s[42:43]
	v_cmp_lt_i32_e64 s[42:43], s47, v137
	s_and_b64 s[42:43], vcc, s[42:43]
	v_cmp_gt_i32_e32 vcc, s39, v37
	v_cndmask_b32_e64 v136, 0, 1.0, s[42:43]
	v_cmp_le_i32_e64 s[42:43], s39, v137
	s_and_b64 s[42:43], vcc, s[42:43]
	v_cmp_ge_i32_e32 vcc, s39, v37
	v_cndmask_b32_e64 v138, 0, 1.0, s[42:43]
	v_cmp_lt_i32_e64 s[42:43], s39, v137
	s_and_b64 s[42:43], vcc, s[42:43]
	v_cmp_ge_i32_e32 vcc, s34, v37
	v_cndmask_b32_e64 v144, 0, 1.0, s[42:43]
	v_cmp_lt_i32_e64 s[42:43], s34, v137
	s_and_b64 s[42:43], vcc, s[42:43]
	v_pk_fma_f32 v[122:123], v[14:15], v[122:123], 0 op_sel_hi:[0,1,0]
	v_cndmask_b32_e64 v146, 0, 1.0, s[42:43]
	v_cmp_ge_i32_e32 vcc, s35, v37
	v_cmp_lt_i32_e64 s[42:43], s35, v137
	v_pk_fma_f32 v[122:123], v[136:137], v[100:101], v[122:123] op_sel_hi:[0,1,1]
	s_and_b64 s[42:43], vcc, s[42:43]
	v_pk_fma_f32 v[122:123], v[138:139], v[66:67], v[122:123] op_sel_hi:[0,1,1]
	v_cndmask_b32_e64 v148, 0, 1.0, s[42:43]
	v_cmp_ge_i32_e32 vcc, s40, v37
	v_cmp_lt_i32_e64 s[42:43], s40, v137
	v_pk_fma_f32 v[122:123], v[144:145], v[92:93], v[122:123] op_sel_hi:[0,1,1]
	s_and_b64 s[42:43], vcc, s[42:43]
	v_pk_fma_f32 v[122:123], v[146:147], v[78:79], v[122:123] op_sel_hi:[0,1,1]
	v_cndmask_b32_e64 v150, 0, 1.0, s[42:43]
	v_pk_fma_f32 v[122:123], v[148:149], v[94:95], v[122:123] op_sel_hi:[0,1,1]
	v_cmp_ge_i32_e32 vcc, s41, v37
	v_cmp_lt_i32_e64 s[42:43], s41, v137
	v_pk_fma_f32 v[120:121], v[14:15], v[120:121], 0 op_sel_hi:[0,1,0]
	v_pk_fma_f32 v[152:153], v[150:151], v[96:97], v[122:123] op_sel_hi:[0,1,1]
	v_pk_fma_f32 v[122:123], v[14:15], v[124:125], 0 op_sel_hi:[0,1,0]
	v_pk_fma_f32 v[14:15], v[14:15], v[126:127], 0 op_sel_hi:[0,1,0]
	s_and_b64 s[42:43], vcc, s[42:43]
	v_pk_fma_f32 v[120:121], v[136:137], v[98:99], v[120:121] op_sel_hi:[0,1,1]
	v_pk_fma_f32 v[122:123], v[136:137], v[104:105], v[122:123] op_sel_hi:[0,1,1]
	v_pk_fma_f32 v[14:15], v[136:137], v[112:113], v[14:15] op_sel_hi:[0,1,1]
	v_cndmask_b32_e64 v136, 0, 1.0, s[42:43]
	v_cmp_ge_i32_e32 vcc, s46, v37
	v_cmp_lt_i32_e64 s[42:43], s46, v137
	s_and_b64 s[42:43], vcc, s[42:43]
	v_pk_fma_f32 v[120:121], v[138:139], v[68:69], v[120:121] op_sel_hi:[0,1,1]
	v_pk_fma_f32 v[122:123], v[138:139], v[64:65], v[122:123] op_sel_hi:[0,1,1]
	v_pk_fma_f32 v[14:15], v[138:139], v[62:63], v[14:15] op_sel_hi:[0,1,1]
	v_cndmask_b32_e64 v138, 0, 1.0, s[42:43]
	v_cmp_ge_i32_e32 vcc, s26, v37
	v_cmp_lt_i32_e64 s[42:43], s26, v137
	s_and_b64 s[42:43], vcc, s[42:43]
	v_pk_fma_f32 v[120:121], v[144:145], v[82:83], v[120:121] op_sel_hi:[0,1,1]
	v_pk_fma_f32 v[122:123], v[144:145], v[54:55], v[122:123] op_sel_hi:[0,1,1]
	v_pk_fma_f32 v[14:15], v[144:145], v[114:115], v[14:15] op_sel_hi:[0,1,1]
	v_cndmask_b32_e64 v144, 0, 1.0, s[42:43]
	v_cmp_ge_i32_e32 vcc, s27, v37
	v_cmp_lt_i32_e64 s[42:43], s27, v137
	s_and_b64 s[42:43], vcc, s[42:43]
	v_pk_fma_f32 v[120:121], v[146:147], v[80:81], v[120:121] op_sel_hi:[0,1,1]
	v_pk_fma_f32 v[122:123], v[146:147], v[74:75], v[122:123] op_sel_hi:[0,1,1]
	v_pk_fma_f32 v[14:15], v[146:147], v[70:71], v[14:15] op_sel_hi:[0,1,1]
	v_cndmask_b32_e64 v146, 0, 1.0, s[42:43]
	v_cmp_ge_i32_e32 vcc, s45, v37
	v_cmp_lt_i32_e64 s[42:43], s45, v137
	s_and_b64 s[42:43], vcc, s[42:43]
	v_pk_fma_f32 v[120:121], v[148:149], v[84:85], v[120:121] op_sel_hi:[0,1,1]
	v_pk_fma_f32 v[122:123], v[148:149], v[58:59], v[122:123] op_sel_hi:[0,1,1]
	v_pk_fma_f32 v[14:15], v[148:149], v[116:117], v[14:15] op_sel_hi:[0,1,1]
	v_cndmask_b32_e64 v148, 0, 1.0, s[42:43]
	v_cmp_ge_i32_e32 vcc, s49, v37
	v_cmp_lt_i32_e64 s[42:43], s49, v137
	v_pk_fma_f32 v[126:127], v[150:151], v[44:45], v[14:15] op_sel_hi:[0,1,1]
	s_and_b64 s[42:43], vcc, s[42:43]
	v_sub_u32_e32 v14, v137, v37
	v_pk_fma_f32 v[120:121], v[150:151], v[86:87], v[120:121] op_sel_hi:[0,1,1]
	v_pk_fma_f32 v[124:125], v[150:151], v[106:107], v[122:123] op_sel_hi:[0,1,1]
	v_cndmask_b32_e64 v150, 0, 1.0, s[42:43]
	v_cmp_ge_i32_e32 vcc, s48, v37
	v_cmp_lt_i32_e64 s[42:43], s48, v137
	v_cvt_f32_i32_e32 v14, v14
	s_and_b64 s[42:43], vcc, s[42:43]
	v_cndmask_b32_e64 v154, 0, 1.0, s[42:43]
	v_cmp_ge_i32_e32 vcc, s31, v37
	v_cmp_lt_i32_e64 s[42:43], s31, v137
	s_and_b64 s[42:43], vcc, s[42:43]
	s_add_i32 s30, s39, 12
	v_cndmask_b32_e64 v156, 0, 1.0, s[42:43]
	v_div_scale_f32 v15, s[42:43], v14, v14, 1.0
	v_cmp_ge_i32_e32 vcc, s30, v37
	v_rcp_f32_e32 v37, v15
	v_cmp_lt_i32_e64 s[42:43], s30, v137
	s_and_b64 s[42:43], vcc, s[42:43]
	v_fma_f32 v122, -v15, v37, 1.0
	v_fmac_f32_e32 v37, v122, v37
	v_div_scale_f32 v122, vcc, 1.0, v14, 1.0
	v_mul_f32_e32 v123, v122, v37
	v_fma_f32 v137, -v15, v123, v122
	v_fmac_f32_e32 v123, v137, v37
	v_fma_f32 v15, -v15, v123, v122
	v_div_fmas_f32 v15, v15, v37, v123
	v_div_fixup_f32 v160, v15, v14, 1.0
	v_pk_fma_f32 v[14:15], v[136:137], v[88:89], v[120:121] op_sel_hi:[0,1,1]
	v_pk_fma_f32 v[14:15], v[138:139], v[90:91], v[14:15] op_sel_hi:[0,1,1]
	v_pk_fma_f32 v[14:15], v[144:145], v[76:77], v[14:15] op_sel_hi:[0,1,1]
	v_pk_fma_f32 v[14:15], v[146:147], v[72:73], v[14:15] op_sel_hi:[0,1,1]
	v_pk_fma_f32 v[14:15], v[148:149], v[60:61], v[14:15] op_sel_hi:[0,1,1]
	v_pk_fma_f32 v[14:15], v[150:151], v[132:133], v[14:15] op_sel_hi:[0,1,1]
	v_pk_fma_f32 v[14:15], v[154:155], v[142:143], v[14:15] op_sel_hi:[0,1,1]
	v_cndmask_b32_e64 v158, 0, 1.0, s[42:43]
	v_pk_fma_f32 v[14:15], v[156:157], v[134:135], v[14:15] op_sel_hi:[0,1,1]
	s_waitcnt vmcnt(7)
	v_and_b32_e32 v123, 0xffff0000, v8
	v_lshlrev_b32_e32 v122, 16, v8
	v_pk_fma_f32 v[14:15], v[158:159], v[122:123], v[14:15] op_sel_hi:[0,1,1]
	v_pk_fma_f32 v[162:163], v[160:161], v[14:15], v[90:91] op_sel_hi:[0,1,1] neg_lo:[0,0,1] neg_hi:[0,0,1]
	v_pk_fma_f32 v[14:15], v[136:137], v[102:103], v[152:153] op_sel_hi:[0,1,1]
	v_pk_fma_f32 v[14:15], v[138:139], v[50:51], v[14:15] op_sel_hi:[0,1,1]
	v_pk_fma_f32 v[14:15], v[144:145], v[38:39], v[14:15] op_sel_hi:[0,1,1]
	v_pk_fma_f32 v[14:15], v[146:147], v[28:29], v[14:15] op_sel_hi:[0,1,1]
	v_pk_fma_f32 v[14:15], v[148:149], v[56:57], v[14:15] op_sel_hi:[0,1,1]
	v_pk_fma_f32 v[14:15], v[150:151], v[130:131], v[14:15] op_sel_hi:[0,1,1]
	v_pk_fma_f32 v[14:15], v[154:155], v[140:141], v[14:15] op_sel_hi:[0,1,1]
	v_pk_fma_f32 v[14:15], v[156:157], v[128:129], v[14:15] op_sel_hi:[0,1,1]
	v_and_b32_e32 v121, 0xffff0000, v9
	v_lshlrev_b32_e32 v120, 16, v9
	v_pk_fma_f32 v[8:9], v[158:159], v[120:121], v[14:15] op_sel_hi:[0,1,1]
	v_pk_fma_f32 v[152:153], v[160:161], v[8:9], v[50:51] op_sel_hi:[0,1,1] neg_lo:[0,0,1] neg_hi:[0,0,1]
	v_pk_fma_f32 v[8:9], v[136:137], v[108:109], v[124:125] op_sel_hi:[0,1,1]
	v_pk_fma_f32 v[8:9], v[138:139], v[110:111], v[8:9] op_sel_hi:[0,1,1]
	v_pk_fma_f32 v[8:9], v[144:145], v[46:47], v[8:9] op_sel_hi:[0,1,1]
	v_pk_fma_f32 v[8:9], v[146:147], v[42:43], v[8:9] op_sel_hi:[0,1,1]
	v_pk_fma_f32 v[8:9], v[148:149], v[48:49], v[8:9] op_sel_hi:[0,1,1]
	v_pk_fma_f32 v[8:9], v[150:151], v[26:27], v[8:9] op_sel_hi:[0,1,1]
	v_pk_fma_f32 v[8:9], v[154:155], v[22:23], v[8:9] op_sel_hi:[0,1,1]
	v_pk_fma_f32 v[8:9], v[156:157], v[18:19], v[8:9] op_sel_hi:[0,1,1]
	v_and_b32_e32 v15, 0xffff0000, v10
	v_lshlrev_b32_e32 v14, 16, v10
	v_pk_fma_f32 v[8:9], v[158:159], v[14:15], v[8:9] op_sel_hi:[0,1,1]
	v_pk_fma_f32 v[164:165], v[160:161], v[8:9], v[110:111] op_sel_hi:[0,1,1] neg_lo:[0,0,1] neg_hi:[0,0,1]
	v_pk_fma_f32 v[8:9], v[136:137], v[118:119], v[126:127] op_sel_hi:[0,1,1]
	v_pk_fma_f32 v[8:9], v[138:139], v[52:53], v[8:9] op_sel_hi:[0,1,1]
	v_pk_fma_f32 v[8:9], v[144:145], v[40:41], v[8:9] op_sel_hi:[0,1,1]
	v_pk_fma_f32 v[8:9], v[146:147], v[30:31], v[8:9] op_sel_hi:[0,1,1]
	v_pk_fma_f32 v[8:9], v[148:149], v[24:25], v[8:9] op_sel_hi:[0,1,1]
	v_pk_fma_f32 v[8:9], v[150:151], v[20:21], v[8:9] op_sel_hi:[0,1,1]
	s_or_b32 s42, s44, 5
	v_pk_fma_f32 v[8:9], v[154:155], v[16:17], v[8:9] op_sel_hi:[0,1,1]
	s_ashr_i32 s43, s42, 31
	v_pk_fma_f32 v[124:125], v[156:157], v[12:13], v[8:9] op_sel_hi:[0,1,1]
	v_and_b32_e32 v9, 0xffff0000, v11
	v_lshlrev_b32_e32 v8, 16, v11
	s_lshl_b64 s[42:43], s[42:43], 11
	v_pk_fma_f32 v[10:11], v[158:159], v[8:9], v[124:125] op_sel_hi:[0,1,1]
	s_add_u32 s42, s52, s42
	v_pk_fma_f32 v[10:11], v[160:161], v[10:11], v[52:53] op_sel_hi:[0,1,1] neg_lo:[0,0,1] neg_hi:[0,0,1]
	s_addc_u32 s43, s53, s43
	v_cvt_pk_bf16_f32 v124, v162, v163
	v_cvt_pk_bf16_f32 v125, v152, v153
	v_cvt_pk_bf16_f32 v126, v164, v165
	v_cvt_pk_bf16_f32 v127, v10, v11
	v_lshl_add_u64 v[10:11], s[42:43], 0, v[34:35]
	global_store_dwordx4 v[10:11], v[124:127], off offset:512
	v_sub_u32_e32 v10, s26, v32
	v_add_u32_e32 v11, s26, v32
	v_max_i32_e32 v37, 0, v10
	v_min_i32_e32 v125, 0x800, v11
	v_cmp_ge_i32_e32 vcc, s47, v37
	v_cmp_lt_i32_e64 s[42:43], s47, v125
	s_and_b64 s[42:43], vcc, s[42:43]
	v_cmp_gt_i32_e32 vcc, s39, v37
	v_cndmask_b32_e64 v10, 0, 1.0, s[42:43]
	v_cmp_le_i32_e64 s[42:43], s39, v125
	s_and_b64 s[42:43], vcc, s[42:43]
	v_cmp_ge_i32_e32 vcc, s39, v37
	v_cndmask_b32_e64 v124, 0, 1.0, s[42:43]
	v_cmp_lt_i32_e64 s[42:43], s39, v125
	s_and_b64 s[42:43], vcc, s[42:43]
	v_cmp_ge_i32_e32 vcc, s34, v37
	v_cndmask_b32_e64 v126, 0, 1.0, s[42:43]
	v_cmp_lt_i32_e64 s[42:43], s34, v125
	s_and_b64 s[42:43], vcc, s[42:43]
	v_cmp_ge_i32_e32 vcc, s35, v37
	v_cndmask_b32_e64 v136, 0, 1.0, s[42:43]
	v_cmp_lt_i32_e64 s[42:43], s35, v125
	s_and_b64 s[42:43], vcc, s[42:43]
	v_cmp_ge_i32_e32 vcc, s40, v37
	v_cndmask_b32_e64 v138, 0, 1.0, s[42:43]
	v_cmp_lt_i32_e64 s[42:43], s40, v125
	s_and_b64 s[42:43], vcc, s[42:43]
	v_cmp_ge_i32_e32 vcc, s41, v37
	v_cndmask_b32_e64 v144, 0, 1.0, s[42:43]
	v_cmp_lt_i32_e64 s[42:43], s41, v125
	s_and_b64 s[42:43], vcc, s[42:43]
	v_cmp_ge_i32_e32 vcc, s46, v37
	v_cndmask_b32_e64 v146, 0, 1.0, s[42:43]
	v_cmp_lt_i32_e64 s[42:43], s46, v125
	s_and_b64 s[42:43], vcc, s[42:43]
	v_pk_fma_f32 v[98:99], v[10:11], v[98:99], 0 op_sel_hi:[0,1,0]
	v_pk_fma_f32 v[100:101], v[10:11], v[100:101], 0 op_sel_hi:[0,1,0]
	v_pk_fma_f32 v[104:105], v[10:11], v[104:105], 0 op_sel_hi:[0,1,0]
	v_pk_fma_f32 v[10:11], v[10:11], v[112:113], 0 op_sel_hi:[0,1,0]
	v_cndmask_b32_e64 v112, 0, 1.0, s[42:43]
	v_cmp_ge_i32_e32 vcc, s26, v37
	v_cmp_lt_i32_e64 s[42:43], s26, v125
	s_and_b64 s[42:43], vcc, s[42:43]
	v_pk_fma_f32 v[98:99], v[124:125], v[68:69], v[98:99] op_sel_hi:[0,1,1]
	v_pk_fma_f32 v[100:101], v[124:125], v[66:67], v[100:101] op_sel_hi:[0,1,1]
	v_pk_fma_f32 v[104:105], v[124:125], v[64:65], v[104:105] op_sel_hi:[0,1,1]
	v_pk_fma_f32 v[10:11], v[124:125], v[62:63], v[10:11] op_sel_hi:[0,1,1]
	v_cndmask_b32_e64 v124, 0, 1.0, s[42:43]
	v_cmp_ge_i32_e32 vcc, s27, v37
	v_cmp_lt_i32_e64 s[42:43], s27, v125
	s_and_b64 s[42:43], vcc, s[42:43]
	v_pk_fma_f32 v[98:99], v[126:127], v[82:83], v[98:99] op_sel_hi:[0,1,1]
	v_pk_fma_f32 v[100:101], v[126:127], v[92:93], v[100:101] op_sel_hi:[0,1,1]
	v_pk_fma_f32 v[104:105], v[126:127], v[54:55], v[104:105] op_sel_hi:[0,1,1]
	v_pk_fma_f32 v[10:11], v[126:127], v[114:115], v[10:11] op_sel_hi:[0,1,1]
	v_cndmask_b32_e64 v126, 0, 1.0, s[42:43]
	v_cmp_ge_i32_e32 vcc, s45, v37
	v_cmp_lt_i32_e64 s[42:43], s45, v125
	s_and_b64 s[42:43], vcc, s[42:43]
	v_pk_fma_f32 v[98:99], v[136:137], v[80:81], v[98:99] op_sel_hi:[0,1,1]
	v_pk_fma_f32 v[100:101], v[136:137], v[78:79], v[100:101] op_sel_hi:[0,1,1]
	v_pk_fma_f32 v[104:105], v[136:137], v[74:75], v[104:105] op_sel_hi:[0,1,1]
	v_pk_fma_f32 v[10:11], v[136:137], v[70:71], v[10:11] op_sel_hi:[0,1,1]
	v_cndmask_b32_e64 v136, 0, 1.0, s[42:43]
	v_cmp_ge_i32_e32 vcc, s49, v37
	v_cmp_lt_i32_e64 s[42:43], s49, v125
	s_and_b64 s[42:43], vcc, s[42:43]
	v_pk_fma_f32 v[98:99], v[138:139], v[84:85], v[98:99] op_sel_hi:[0,1,1]
	v_pk_fma_f32 v[100:101], v[138:139], v[94:95], v[100:101] op_sel_hi:[0,1,1]
	v_pk_fma_f32 v[104:105], v[138:139], v[58:59], v[104:105] op_sel_hi:[0,1,1]
	v_pk_fma_f32 v[10:11], v[138:139], v[116:117], v[10:11] op_sel_hi:[0,1,1]
	v_cndmask_b32_e64 v138, 0, 1.0, s[42:43]
	v_cmp_ge_i32_e32 vcc, s48, v37
	v_cmp_lt_i32_e64 s[42:43], s48, v125
	s_and_b64 s[42:43], vcc, s[42:43]
	v_sub_u32_e32 v113, v125, v37
	v_pk_fma_f32 v[98:99], v[144:145], v[86:87], v[98:99] op_sel_hi:[0,1,1]
	v_pk_fma_f32 v[100:101], v[144:145], v[96:97], v[100:101] op_sel_hi:[0,1,1]
	v_pk_fma_f32 v[104:105], v[144:145], v[106:107], v[104:105] op_sel_hi:[0,1,1]
	v_pk_fma_f32 v[10:11], v[144:145], v[44:45], v[10:11] op_sel_hi:[0,1,1]
	v_cndmask_b32_e64 v144, 0, 1.0, s[42:43]
	v_cmp_ge_i32_e32 vcc, s31, v37
	v_cmp_lt_i32_e64 s[42:43], s31, v125
	v_cvt_f32_i32_e32 v113, v113
	s_and_b64 s[42:43], vcc, s[42:43]
	v_pk_fma_f32 v[98:99], v[146:147], v[88:89], v[98:99] op_sel_hi:[0,1,1]
	v_pk_fma_f32 v[100:101], v[146:147], v[102:103], v[100:101] op_sel_hi:[0,1,1]
	v_pk_fma_f32 v[104:105], v[146:147], v[108:109], v[104:105] op_sel_hi:[0,1,1]
	v_pk_fma_f32 v[10:11], v[146:147], v[118:119], v[10:11] op_sel_hi:[0,1,1]
	v_cndmask_b32_e64 v146, 0, 1.0, s[42:43]
	v_cmp_ge_i32_e32 vcc, s30, v37
	v_cmp_lt_i32_e64 s[42:43], s30, v125
	s_and_b64 s[42:43], vcc, s[42:43]
	s_add_i32 s47, s39, 13
	v_cndmask_b32_e64 v148, 0, 1.0, s[42:43]
	v_cmp_ge_i32_e32 vcc, s47, v37
	v_div_scale_f32 v37, s[42:43], v113, v113, 1.0
	v_rcp_f32_e32 v127, v37
	v_cmp_lt_i32_e64 s[42:43], s47, v125
	s_and_b64 s[42:43], vcc, s[42:43]
	v_pk_fma_f32 v[100:101], v[112:113], v[50:51], v[100:101] op_sel_hi:[0,1,1]
	v_fma_f32 v125, -v37, v127, 1.0
	v_fmac_f32_e32 v127, v125, v127
	v_div_scale_f32 v125, vcc, 1.0, v113, 1.0
	v_mul_f32_e32 v137, v125, v127
	v_fma_f32 v139, -v37, v137, v125
	v_pk_fma_f32 v[100:101], v[124:125], v[38:39], v[100:101] op_sel_hi:[0,1,1]
	v_fmac_f32_e32 v137, v139, v127
	v_pk_fma_f32 v[100:101], v[126:127], v[28:29], v[100:101] op_sel_hi:[0,1,1]
	v_pk_fma_f32 v[100:101], v[136:137], v[56:57], v[100:101] op_sel_hi:[0,1,1]
	v_pk_fma_f32 v[100:101], v[138:139], v[130:131], v[100:101] op_sel_hi:[0,1,1]
	v_pk_fma_f32 v[100:101], v[144:145], v[140:141], v[100:101] op_sel_hi:[0,1,1]
	v_fma_f32 v37, -v37, v137, v125
	v_pk_fma_f32 v[100:101], v[146:147], v[128:129], v[100:101] op_sel_hi:[0,1,1]
	v_cndmask_b32_e64 v150, 0, 1.0, s[42:43]
	v_div_fmas_f32 v37, v37, v127, v137
	v_pk_fma_f32 v[100:101], v[148:149], v[120:121], v[100:101] op_sel_hi:[0,1,1]
	s_waitcnt vmcnt(7)
	v_and_b32_e32 v157, 0xffff0000, v5
	v_lshlrev_b32_e32 v156, 16, v5
	v_div_fixup_f32 v152, v37, v113, 1.0
	v_and_b32_e32 v155, 0xffff0000, v4
	v_lshlrev_b32_e32 v154, 16, v4
	v_pk_fma_f32 v[4:5], v[150:151], v[156:157], v[100:101] op_sel_hi:[0,1,1]
	v_pk_fma_f32 v[100:101], v[152:153], v[4:5], v[38:39] op_sel_hi:[0,1,1] neg_lo:[0,0,1] neg_hi:[0,0,1]
	v_pk_fma_f32 v[4:5], v[112:113], v[110:111], v[104:105] op_sel_hi:[0,1,1]
	v_pk_fma_f32 v[4:5], v[124:125], v[46:47], v[4:5] op_sel_hi:[0,1,1]
	v_pk_fma_f32 v[4:5], v[126:127], v[42:43], v[4:5] op_sel_hi:[0,1,1]
	v_pk_fma_f32 v[4:5], v[136:137], v[48:49], v[4:5] op_sel_hi:[0,1,1]
	v_pk_fma_f32 v[4:5], v[138:139], v[26:27], v[4:5] op_sel_hi:[0,1,1]
	v_pk_fma_f32 v[4:5], v[144:145], v[22:23], v[4:5] op_sel_hi:[0,1,1]
	v_pk_fma_f32 v[4:5], v[146:147], v[18:19], v[4:5] op_sel_hi:[0,1,1]
	v_pk_fma_f32 v[4:5], v[148:149], v[14:15], v[4:5] op_sel_hi:[0,1,1]
	v_and_b32_e32 v105, 0xffff0000, v6
	v_lshlrev_b32_e32 v104, 16, v6
	v_pk_fma_f32 v[4:5], v[150:151], v[104:105], v[4:5] op_sel_hi:[0,1,1]
	v_pk_fma_f32 v[98:99], v[112:113], v[90:91], v[98:99] op_sel_hi:[0,1,1]
	v_pk_fma_f32 v[158:159], v[152:153], v[4:5], v[46:47] op_sel_hi:[0,1,1] neg_lo:[0,0,1] neg_hi:[0,0,1]
	v_pk_fma_f32 v[4:5], v[112:113], v[52:53], v[10:11] op_sel_hi:[0,1,1]
	v_pk_fma_f32 v[98:99], v[124:125], v[76:77], v[98:99] op_sel_hi:[0,1,1]
	v_pk_fma_f32 v[4:5], v[124:125], v[40:41], v[4:5] op_sel_hi:[0,1,1]
	v_pk_fma_f32 v[98:99], v[126:127], v[72:73], v[98:99] op_sel_hi:[0,1,1]
	v_pk_fma_f32 v[4:5], v[126:127], v[30:31], v[4:5] op_sel_hi:[0,1,1]
	v_pk_fma_f32 v[98:99], v[136:137], v[60:61], v[98:99] op_sel_hi:[0,1,1]
	v_pk_fma_f32 v[4:5], v[136:137], v[24:25], v[4:5] op_sel_hi:[0,1,1]
	v_pk_fma_f32 v[98:99], v[138:139], v[132:133], v[98:99] op_sel_hi:[0,1,1]
	v_pk_fma_f32 v[4:5], v[138:139], v[20:21], v[4:5] op_sel_hi:[0,1,1]
	v_pk_fma_f32 v[98:99], v[144:145], v[142:143], v[98:99] op_sel_hi:[0,1,1]
	v_pk_fma_f32 v[4:5], v[144:145], v[16:17], v[4:5] op_sel_hi:[0,1,1]
	s_or_b32 s42, s44, 6
	v_pk_fma_f32 v[98:99], v[146:147], v[134:135], v[98:99] op_sel_hi:[0,1,1]
	v_pk_fma_f32 v[4:5], v[146:147], v[12:13], v[4:5] op_sel_hi:[0,1,1]
	s_ashr_i32 s43, s42, 31
	v_pk_fma_f32 v[98:99], v[148:149], v[122:123], v[98:99] op_sel_hi:[0,1,1]
	v_pk_fma_f32 v[4:5], v[148:149], v[8:9], v[4:5] op_sel_hi:[0,1,1]
	v_and_b32_e32 v11, 0xffff0000, v7
	v_lshlrev_b32_e32 v10, 16, v7
	s_lshl_b64 s[42:43], s[42:43], 11
	v_pk_fma_f32 v[98:99], v[150:151], v[154:155], v[98:99] op_sel_hi:[0,1,1]
	v_pk_fma_f32 v[4:5], v[150:151], v[10:11], v[4:5] op_sel_hi:[0,1,1]
	s_add_u32 s42, s52, s42
	v_pk_fma_f32 v[98:99], v[152:153], v[98:99], v[76:77] op_sel_hi:[0,1,1] neg_lo:[0,0,1] neg_hi:[0,0,1]
	v_pk_fma_f32 v[112:113], v[152:153], v[4:5], v[40:41] op_sel_hi:[0,1,1] neg_lo:[0,0,1] neg_hi:[0,0,1]
	s_addc_u32 s43, s53, s43
	v_cvt_pk_bf16_f32 v4, v98, v99
	v_cvt_pk_bf16_f32 v5, v100, v101
	v_cvt_pk_bf16_f32 v6, v158, v159
	v_cvt_pk_bf16_f32 v7, v112, v113
	v_lshl_add_u64 v[98:99], s[42:43], 0, v[34:35]
	global_store_dwordx4 v[98:99], v[4:7], off offset:512
	s_nop 1
	v_sub_u32_e32 v4, s27, v32
	v_add_u32_e32 v5, s27, v32
	v_max_i32_e32 v7, 0, v4
	v_min_i32_e32 v37, 0x800, v5
	v_cmp_gt_i32_e32 vcc, s39, v7
	v_cmp_le_i32_e64 s[42:43], s39, v37
	s_and_b64 s[42:43], vcc, s[42:43]
	v_cmp_ge_i32_e32 vcc, s39, v7
	v_cndmask_b32_e64 v4, 0, 1.0, s[42:43]
	v_cmp_lt_i32_e64 s[42:43], s39, v37
	s_and_b64 s[42:43], vcc, s[42:43]
	v_cmp_ge_i32_e32 vcc, s34, v7
	v_cndmask_b32_e64 v6, 0, 1.0, s[42:43]
	v_cmp_lt_i32_e64 s[42:43], s34, v37
	s_and_b64 s[42:43], vcc, s[42:43]
	v_cmp_ge_i32_e32 vcc, s35, v7
	v_cndmask_b32_e64 v32, 0, 1.0, s[42:43]
	v_cmp_lt_i32_e64 s[42:43], s35, v37
	s_and_b64 s[34:35], vcc, s[42:43]
	v_cmp_ge_i32_e32 vcc, s40, v7
	v_cmp_lt_i32_e64 s[42:43], s40, v37
	v_cndmask_b32_e64 v98, 0, 1.0, s[34:35]
	s_and_b64 s[34:35], vcc, s[42:43]
	v_cmp_ge_i32_e32 vcc, s41, v7
	v_cmp_lt_i32_e64 s[42:43], s41, v37
	v_cndmask_b32_e64 v100, 0, 1.0, s[34:35]
	s_and_b64 s[34:35], vcc, s[42:43]
	v_cmp_ge_i32_e32 vcc, s46, v7
	v_cmp_lt_i32_e64 s[42:43], s46, v37
	v_pk_fma_f32 v[68:69], v[4:5], v[68:69], 0 op_sel_hi:[0,1,0]
	v_pk_fma_f32 v[66:67], v[4:5], v[66:67], 0 op_sel_hi:[0,1,0]
	v_pk_fma_f32 v[64:65], v[4:5], v[64:65], 0 op_sel_hi:[0,1,0]
	v_pk_fma_f32 v[4:5], v[4:5], v[62:63], 0 op_sel_hi:[0,1,0]
	v_cndmask_b32_e64 v112, 0, 1.0, s[34:35]
	s_and_b64 s[34:35], vcc, s[42:43]
	v_pk_fma_f32 v[4:5], v[6:7], v[114:115], v[4:5] op_sel_hi:[0,1,1]
	v_cmp_ge_i32_e32 vcc, s26, v7
	v_cmp_lt_i32_e64 s[42:43], s26, v37
	v_cndmask_b32_e64 v124, 0, 1.0, s[34:35]
	v_pk_fma_f32 v[4:5], v[32:33], v[70:71], v[4:5] op_sel_hi:[0,1,1]
	s_and_b64 s[34:35], vcc, s[42:43]
	v_cmp_ge_i32_e32 vcc, s27, v7
	v_cmp_lt_i32_e64 s[42:43], s27, v37
	v_pk_fma_f32 v[68:69], v[6:7], v[82:83], v[68:69] op_sel_hi:[0,1,1]
	v_pk_fma_f32 v[66:67], v[6:7], v[92:93], v[66:67] op_sel_hi:[0,1,1]
	v_pk_fma_f32 v[54:55], v[6:7], v[54:55], v[64:65] op_sel_hi:[0,1,1]
	v_pk_fma_f32 v[4:5], v[98:99], v[116:117], v[4:5] op_sel_hi:[0,1,1]
	s_and_b64 s[26:27], vcc, s[42:43]
	v_cmp_ge_i32_e32 vcc, s45, v7
	v_cmp_lt_i32_e64 s[42:43], s45, v37
	v_pk_fma_f32 v[68:69], v[32:33], v[80:81], v[68:69] op_sel_hi:[0,1,1]
	v_pk_fma_f32 v[66:67], v[32:33], v[78:79], v[66:67] op_sel_hi:[0,1,1]
	v_pk_fma_f32 v[54:55], v[32:33], v[74:75], v[54:55] op_sel_hi:[0,1,1]
	v_pk_fma_f32 v[4:5], v[100:101], v[44:45], v[4:5] op_sel_hi:[0,1,1]
	v_cndmask_b32_e64 v32, 0, 1.0, s[26:27]
	s_and_b64 s[26:27], vcc, s[42:43]
	v_cmp_ge_i32_e32 vcc, s49, v7
	v_cmp_lt_i32_e64 s[42:43], s49, v37
	v_pk_fma_f32 v[4:5], v[112:113], v[118:119], v[4:5] op_sel_hi:[0,1,1]
	v_cndmask_b32_e64 v44, 0, 1.0, s[26:27]
	s_and_b64 s[26:27], vcc, s[42:43]
	v_cmp_ge_i32_e32 vcc, s48, v7
	v_cmp_lt_i32_e64 s[42:43], s48, v37
	v_sub_u32_e32 v45, v37, v7
	v_pk_fma_f32 v[4:5], v[124:125], v[52:53], v[4:5] op_sel_hi:[0,1,1]
	v_cndmask_b32_e64 v52, 0, 1.0, s[26:27]
	s_and_b64 s[26:27], vcc, s[42:43]
	v_cmp_ge_i32_e32 vcc, s31, v7
	v_cmp_lt_i32_e64 s[42:43], s31, v37
	v_cvt_f32_i32_e32 v45, v45
	v_pk_fma_f32 v[66:67], v[98:99], v[94:95], v[66:67] op_sel_hi:[0,1,1]
	v_pk_fma_f32 v[54:55], v[98:99], v[58:59], v[54:55] op_sel_hi:[0,1,1]
	v_cndmask_b32_e64 v58, 0, 1.0, s[26:27]
	s_and_b64 s[26:27], vcc, s[42:43]
	v_cmp_ge_i32_e32 vcc, s30, v7
	v_cmp_lt_i32_e64 s[42:43], s30, v37
	v_pk_fma_f32 v[66:67], v[100:101], v[96:97], v[66:67] op_sel_hi:[0,1,1]
	v_cndmask_b32_e64 v62, 0, 1.0, s[26:27]
	s_and_b64 s[26:27], vcc, s[42:43]
	v_cmp_ge_i32_e32 vcc, s47, v7
	v_cmp_lt_i32_e64 s[42:43], s47, v37
	v_pk_fma_f32 v[66:67], v[112:113], v[102:103], v[66:67] op_sel_hi:[0,1,1]
	v_cndmask_b32_e64 v64, 0, 1.0, s[26:27]
	s_and_b64 s[26:27], vcc, s[42:43]
	s_add_i32 s30, s39, 14
	v_pk_fma_f32 v[50:51], v[124:125], v[50:51], v[66:67] op_sel_hi:[0,1,1]
	v_cndmask_b32_e64 v66, 0, 1.0, s[26:27]
	v_cmp_ge_i32_e32 vcc, s30, v7
	v_div_scale_f32 v7, s[26:27], v45, v45, 1.0
	v_rcp_f32_e32 v53, v7
	v_cmp_lt_i32_e64 s[42:43], s30, v37
	s_and_b64 s[26:27], vcc, s[42:43]
	v_cndmask_b32_e64 v6, 0, 1.0, s[34:35]
	v_fma_f32 v37, -v7, v53, 1.0
	v_fmac_f32_e32 v53, v37, v53
	v_div_scale_f32 v37, vcc, 1.0, v45, 1.0
	v_mul_f32_e32 v59, v37, v53
	v_fma_f32 v63, -v7, v59, v37
	v_fmac_f32_e32 v59, v63, v53
	v_fma_f32 v7, -v7, v59, v37
	v_div_fmas_f32 v7, v7, v53, v59
	v_pk_fma_f32 v[38:39], v[6:7], v[38:39], v[50:51] op_sel_hi:[0,1,1]
	v_pk_fma_f32 v[38:39], v[32:33], v[28:29], v[38:39] op_sel_hi:[0,1,1]
	v_pk_fma_f32 v[68:69], v[98:99], v[84:85], v[68:69] op_sel_hi:[0,1,1]
	v_pk_fma_f32 v[38:39], v[44:45], v[56:57], v[38:39] op_sel_hi:[0,1,1]
	v_pk_fma_f32 v[68:69], v[100:101], v[86:87], v[68:69] op_sel_hi:[0,1,1]
	v_pk_fma_f32 v[38:39], v[52:53], v[130:131], v[38:39] op_sel_hi:[0,1,1]
	v_pk_fma_f32 v[68:69], v[112:113], v[88:89], v[68:69] op_sel_hi:[0,1,1]
	v_pk_fma_f32 v[38:39], v[58:59], v[140:141], v[38:39] op_sel_hi:[0,1,1]
	v_pk_fma_f32 v[68:69], v[124:125], v[90:91], v[68:69] op_sel_hi:[0,1,1]
	v_pk_fma_f32 v[38:39], v[62:63], v[128:129], v[38:39] op_sel_hi:[0,1,1]
	v_pk_fma_f32 v[54:55], v[100:101], v[106:107], v[54:55] op_sel_hi:[0,1,1]
	v_pk_fma_f32 v[68:69], v[6:7], v[76:77], v[68:69] op_sel_hi:[0,1,1]
	v_pk_fma_f32 v[38:39], v[64:65], v[120:121], v[38:39] op_sel_hi:[0,1,1]
	v_pk_fma_f32 v[54:55], v[112:113], v[108:109], v[54:55] op_sel_hi:[0,1,1]
	v_cndmask_b32_e64 v70, 0, 1.0, s[26:27]
	v_pk_fma_f32 v[68:69], v[32:33], v[72:73], v[68:69] op_sel_hi:[0,1,1]
	v_pk_fma_f32 v[38:39], v[66:67], v[156:157], v[38:39] op_sel_hi:[0,1,1]
	s_waitcnt vmcnt(5)
	v_and_b32_e32 v51, 0xffff0000, v1
	v_lshlrev_b32_e32 v50, 16, v1
	v_pk_fma_f32 v[54:55], v[124:125], v[110:111], v[54:55] op_sel_hi:[0,1,1]
	v_div_fixup_f32 v74, v7, v45, 1.0
	v_pk_fma_f32 v[60:61], v[44:45], v[60:61], v[68:69] op_sel_hi:[0,1,1]
	v_and_b32_e32 v69, 0xffff0000, v0
	v_lshlrev_b32_e32 v68, 16, v0
	v_pk_fma_f32 v[0:1], v[70:71], v[50:51], v[38:39] op_sel_hi:[0,1,1]
	v_pk_fma_f32 v[28:29], v[74:75], v[0:1], v[28:29] op_sel_hi:[0,1,1] neg_lo:[0,0,1] neg_hi:[0,0,1]
	v_pk_fma_f32 v[0:1], v[6:7], v[46:47], v[54:55] op_sel_hi:[0,1,1]
	v_pk_fma_f32 v[0:1], v[32:33], v[42:43], v[0:1] op_sel_hi:[0,1,1]
	v_pk_fma_f32 v[0:1], v[44:45], v[48:49], v[0:1] op_sel_hi:[0,1,1]
	v_pk_fma_f32 v[0:1], v[52:53], v[26:27], v[0:1] op_sel_hi:[0,1,1]
	v_pk_fma_f32 v[0:1], v[58:59], v[22:23], v[0:1] op_sel_hi:[0,1,1]
	v_pk_fma_f32 v[0:1], v[62:63], v[18:19], v[0:1] op_sel_hi:[0,1,1]
	v_pk_fma_f32 v[0:1], v[64:65], v[14:15], v[0:1] op_sel_hi:[0,1,1]
	v_pk_fma_f32 v[0:1], v[66:67], v[104:105], v[0:1] op_sel_hi:[0,1,1]
	v_and_b32_e32 v15, 0xffff0000, v2
	v_lshlrev_b32_e32 v14, 16, v2
	v_pk_fma_f32 v[0:1], v[70:71], v[14:15], v[0:1] op_sel_hi:[0,1,1]
	v_pk_fma_f32 v[14:15], v[74:75], v[0:1], v[42:43] op_sel_hi:[0,1,1] neg_lo:[0,0,1] neg_hi:[0,0,1]
	v_pk_fma_f32 v[0:1], v[6:7], v[40:41], v[4:5] op_sel_hi:[0,1,1]
	v_pk_fma_f32 v[0:1], v[32:33], v[30:31], v[0:1] op_sel_hi:[0,1,1]
	v_pk_fma_f32 v[0:1], v[44:45], v[24:25], v[0:1] op_sel_hi:[0,1,1]
	v_pk_fma_f32 v[60:61], v[52:53], v[132:133], v[60:61] op_sel_hi:[0,1,1]
	v_pk_fma_f32 v[0:1], v[52:53], v[20:21], v[0:1] op_sel_hi:[0,1,1]
	v_pk_fma_f32 v[60:61], v[58:59], v[142:143], v[60:61] op_sel_hi:[0,1,1]
	v_pk_fma_f32 v[0:1], v[58:59], v[16:17], v[0:1] op_sel_hi:[0,1,1]
	v_pk_fma_f32 v[60:61], v[62:63], v[134:135], v[60:61] op_sel_hi:[0,1,1]
	v_pk_fma_f32 v[0:1], v[62:63], v[12:13], v[0:1] op_sel_hi:[0,1,1]
	s_or_b32 s26, s44, 7
	v_pk_fma_f32 v[60:61], v[64:65], v[122:123], v[60:61] op_sel_hi:[0,1,1]
	v_pk_fma_f32 v[0:1], v[64:65], v[8:9], v[0:1] op_sel_hi:[0,1,1]
	s_ashr_i32 s27, s26, 31
	v_pk_fma_f32 v[60:61], v[66:67], v[154:155], v[60:61] op_sel_hi:[0,1,1]
	v_pk_fma_f32 v[0:1], v[66:67], v[10:11], v[0:1] op_sel_hi:[0,1,1]
	v_and_b32_e32 v5, 0xffff0000, v3
	v_lshlrev_b32_e32 v4, 16, v3
	s_lshl_b64 s[26:27], s[26:27], 11
	v_pk_fma_f32 v[60:61], v[70:71], v[68:69], v[60:61] op_sel_hi:[0,1,1]
	v_pk_fma_f32 v[0:1], v[70:71], v[4:5], v[0:1] op_sel_hi:[0,1,1]
	s_add_u32 s26, s52, s26
	v_pk_fma_f32 v[60:61], v[74:75], v[60:61], v[72:73] op_sel_hi:[0,1,1] neg_lo:[0,0,1] neg_hi:[0,0,1]
	v_pk_fma_f32 v[4:5], v[74:75], v[0:1], v[30:31] op_sel_hi:[0,1,1] neg_lo:[0,0,1] neg_hi:[0,0,1]
	s_addc_u32 s27, s53, s27
	v_cvt_pk_bf16_f32 v0, v60, v61
	v_cvt_pk_bf16_f32 v1, v28, v29
	v_cvt_pk_bf16_f32 v2, v14, v15
	v_cvt_pk_bf16_f32 v3, v4, v5
	v_lshl_add_u64 v[4:5], s[26:27], 0, v[34:35]
	global_store_dwordx4 v[4:5], v[0:3], off offset:512
.LBB0_402:
	s_andn2_saveexec_b64 s[24:25], s[24:25]
	s_cbranch_execz .LBB0_404
	v_readlane_b32 s26, v201, 0
	v_readlane_b32 s27, v201, 1
	v_readlane_b32 s30, v201, 2
	v_readlane_b32 s31, v201, 3
	v_readlane_b32 s34, v201, 4
	v_readlane_b32 s35, v201, 5
	v_readlane_b32 s40, v201, 6
	v_readlane_b32 s41, v201, 7
	v_readlane_b32 s42, v201, 8
	v_readlane_b32 s43, v201, 9
	v_readlane_b32 s44, v201, 10
	v_readlane_b32 s45, v201, 11
	v_readlane_b32 s46, v201, 12
	v_readlane_b32 s47, v201, 13
	v_readlane_b32 s48, v201, 14
	v_readlane_b32 s49, v201, 15
	v_readlane_b32 s50, v201, 16
	v_readlane_b32 s51, v201, 17
	v_readlane_b32 s52, v201, 18
	v_readlane_b32 s53, v201, 19
	v_readlane_b32 s54, v201, 20
	v_readlane_b32 s55, v201, 21
	v_readlane_b32 s56, v201, 22
	v_readlane_b32 s57, v201, 23
	s_nop 4
	s_waitcnt vmcnt(31)
	v_and_b32_e32 v149, 0xffff0000, v130
	v_lshlrev_b32_e32 v148, 16, v130
	v_lshl_add_u64 v[34:35], s[46:47], 0, v[34:35]
	s_add_i32 s46, s0, -1
	s_cmpk_lt_u32 s46, 0x100
	s_cselect_b64 s[46:47], -1, 0
	s_cmpk_lt_u32 s39, 0x800
	v_cndmask_b32_e64 v142, 0, 1.0, s[46:47]
	s_cselect_b64 s[46:47], -1, 0
	s_cmp_gt_i32 s0, -1
	v_cndmask_b32_e64 v144, 0, 1.0, s[46:47]
	s_cselect_b64 s[46:47], -1, 0
	s_cmpk_lt_i32 s57, 0x801
	s_cselect_b64 s[58:59], -1, 0
	s_waitcnt vmcnt(30)
	v_and_b32_e32 v151, 0xffff0000, v122
	v_lshlrev_b32_e32 v150, 16, v122
	s_and_b64 s[58:59], s[46:47], s[58:59]
	v_pk_mul_f32 v[148:149], v[148:149], v[150:151]
	s_waitcnt vmcnt(29)
	v_and_b32_e32 v151, 0xffff0000, v118
	v_lshlrev_b32_e32 v150, 16, v118
	s_waitcnt vmcnt(28)
	v_and_b32_e32 v153, 0xffff0000, v110
	v_lshlrev_b32_e32 v152, 16, v110
	v_cndmask_b32_e64 v32, 0, 1.0, s[58:59]
	v_pk_mul_f32 v[150:151], v[150:151], v[152:153]
	s_waitcnt vmcnt(27)
	v_and_b32_e32 v153, 0xffff0000, v114
	v_lshlrev_b32_e32 v152, 16, v114
	s_waitcnt vmcnt(12)
	v_pk_mul_f32 v[146:147], v[142:143], v[28:29] op_sel_hi:[0,1]
	v_pk_fma_f32 v[146:147], v[148:149], v[146:147], 0 op_sel_hi:[1,1,0]
	s_waitcnt vmcnt(8)
	v_pk_mul_f32 v[148:149], v[144:145], v[38:39] op_sel_hi:[0,1]
	v_and_b32_e32 v155, 0xffff0000, v106
	v_lshlrev_b32_e32 v154, 16, v106
	v_pk_fma_f32 v[146:147], v[150:151], v[148:149], v[146:147]
	s_waitcnt vmcnt(6)
	v_pk_mul_f32 v[148:149], v[32:33], v[46:47] op_sel_hi:[0,1]
	v_pk_mul_f32 v[152:153], v[152:153], v[154:155]
	v_lshlrev_b32_e32 v130, 16, v123
	v_pk_fma_f32 v[146:147], v[152:153], v[148:149], v[146:147]
	s_waitcnt vmcnt(5)
	v_and_b32_e32 v149, 0xffff0000, v138
	v_lshlrev_b32_e32 v148, 16, v138
	v_pk_mul_f32 v[146:147], v[146:147], v[148:149]
	v_and_b32_e32 v149, 0xffff0000, v131
	v_lshlrev_b32_e32 v148, 16, v131
	v_and_b32_e32 v131, 0xffff0000, v123
	v_cvt_pk_bf16_f32 v106, v146, v147
	v_pk_mul_f32 v[146:147], v[142:143], v[30:31] op_sel_hi:[0,1]
	v_pk_mul_f32 v[122:123], v[148:149], v[130:131]
	v_lshlrev_b32_e32 v118, 16, v111
	v_pk_fma_f32 v[122:123], v[122:123], v[146:147], 0 op_sel_hi:[1,1,0]
	v_and_b32_e32 v147, 0xffff0000, v119
	v_lshlrev_b32_e32 v146, 16, v119
	v_and_b32_e32 v119, 0xffff0000, v111
	v_pk_mul_f32 v[130:131], v[144:145], v[40:41] op_sel_hi:[0,1]
	v_pk_mul_f32 v[110:111], v[146:147], v[118:119]
	v_lshlrev_b32_e32 v114, 16, v107
	v_pk_fma_f32 v[118:119], v[110:111], v[130:131], v[122:123]
	v_and_b32_e32 v131, 0xffff0000, v115
	v_lshlrev_b32_e32 v130, 16, v115
	v_and_b32_e32 v115, 0xffff0000, v107
	v_pk_mul_f32 v[122:123], v[32:33], v[48:49] op_sel_hi:[0,1]
	v_pk_mul_f32 v[114:115], v[130:131], v[114:115]
	v_and_b32_e32 v131, 0xffff0000, v124
	v_pk_fma_f32 v[118:119], v[114:115], v[122:123], v[118:119]
	v_and_b32_e32 v123, 0xffff0000, v139
	v_lshlrev_b32_e32 v122, 16, v139
	v_pk_mul_f32 v[118:119], v[118:119], v[122:123]
	v_and_b32_e32 v123, 0xffff0000, v132
	v_lshlrev_b32_e32 v122, 16, v132
	v_lshlrev_b32_e32 v130, 16, v124
	v_cvt_pk_bf16_f32 v107, v118, v119
	v_pk_mul_f32 v[118:119], v[142:143], v[16:17] op_sel_hi:[0,1]
	v_pk_mul_f32 v[122:123], v[122:123], v[130:131]
	v_and_b32_e32 v131, 0xffff0000, v120
	v_lshlrev_b32_e32 v130, 16, v120
	v_and_b32_e32 v139, 0xffff0000, v112
	v_lshlrev_b32_e32 v138, 16, v112
	v_pk_fma_f32 v[118:119], v[122:123], v[118:119], 0 op_sel_hi:[1,1,0]
	v_pk_mul_f32 v[122:123], v[144:145], v[20:21] op_sel_hi:[0,1]
	v_pk_mul_f32 v[130:131], v[130:131], v[138:139]
	v_and_b32_e32 v139, 0xffff0000, v116
	v_lshlrev_b32_e32 v138, 16, v116
	v_and_b32_e32 v147, 0xffff0000, v108
	v_lshlrev_b32_e32 v146, 16, v108
	v_pk_fma_f32 v[118:119], v[130:131], v[122:123], v[118:119]
	v_pk_mul_f32 v[122:123], v[32:33], v[24:25] op_sel_hi:[0,1]
	v_pk_mul_f32 v[138:139], v[138:139], v[146:147]
	v_lshlrev_b32_e32 v132, 16, v125
	v_pk_fma_f32 v[118:119], v[138:139], v[122:123], v[118:119]
	v_and_b32_e32 v123, 0xffff0000, v140
	v_lshlrev_b32_e32 v122, 16, v140
	v_pk_mul_f32 v[118:119], v[118:119], v[122:123]
	v_and_b32_e32 v123, 0xffff0000, v133
	v_lshlrev_b32_e32 v122, 16, v133
	v_and_b32_e32 v133, 0xffff0000, v125
	v_cvt_pk_bf16_f32 v108, v118, v119
	v_pk_mul_f32 v[118:119], v[142:143], v[18:19] op_sel_hi:[0,1]
	v_pk_mul_f32 v[122:123], v[122:123], v[132:133]
	v_and_b32_e32 v125, 0xffff0000, v121
	v_lshlrev_b32_e32 v124, 16, v121
	v_and_b32_e32 v121, 0xffff0000, v113
	v_lshlrev_b32_e32 v120, 16, v113
	v_pk_fma_f32 v[118:119], v[122:123], v[118:119], 0 op_sel_hi:[1,1,0]
	v_pk_mul_f32 v[122:123], v[144:145], v[22:23] op_sel_hi:[0,1]
	v_pk_mul_f32 v[112:113], v[124:125], v[120:121]
	v_lshlrev_b32_e32 v116, 16, v109
	v_pk_fma_f32 v[118:119], v[112:113], v[122:123], v[118:119]
	v_and_b32_e32 v123, 0xffff0000, v117
	v_lshlrev_b32_e32 v122, 16, v117
	v_and_b32_e32 v117, 0xffff0000, v109
	v_pk_mul_f32 v[120:121], v[32:33], v[26:27] op_sel_hi:[0,1]
	v_pk_mul_f32 v[116:117], v[122:123], v[116:117]
	s_cmpk_lt_i32 s56, 0x801
	v_pk_fma_f32 v[118:119], v[116:117], v[120:121], v[118:119]
	v_and_b32_e32 v121, 0xffff0000, v141
	v_lshlrev_b32_e32 v120, 16, v141
	v_pk_mul_f32 v[118:119], v[118:119], v[120:121]
	global_load_dwordx4 v[58:61], v[42:43], off offset:512
	s_nop 0
	global_load_dwordx4 v[42:45], v[44:45], off offset:512
	v_cvt_pk_bf16_f32 v109, v118, v119
	v_lshl_add_u64 v[118:119], v[34:35], 0, s[54:55]
	s_cselect_b64 s[54:55], -1, 0
	global_store_dwordx4 v[118:119], v[106:109], off
	s_and_b64 s[54:55], s[46:47], s[54:55]
	v_pk_mul_f32 v[118:119], v[32:33], v[38:39] op_sel_hi:[0,1]
	v_pk_mul_f32 v[108:109], v[144:145], v[28:29] op_sel_hi:[0,1]
	v_cndmask_b32_e64 v106, 0, 1.0, s[54:55]
	v_pk_fma_f32 v[108:109], v[150:151], v[108:109], 0 op_sel_hi:[1,1,0]
	v_and_b32_e32 v121, 0xffff0000, v102
	v_lshlrev_b32_e32 v120, 16, v102
	v_and_b32_e32 v123, 0xffff0000, v98
	v_lshlrev_b32_e32 v122, 16, v98
	v_pk_fma_f32 v[108:109], v[152:153], v[118:119], v[108:109]
	v_pk_mul_f32 v[118:119], v[106:107], v[46:47] op_sel_hi:[0,1]
	v_pk_mul_f32 v[120:121], v[120:121], v[122:123]
	v_lshlrev_b32_e32 v102, 16, v99
	v_pk_fma_f32 v[108:109], v[120:121], v[118:119], v[108:109]
	s_waitcnt vmcnt(7)
	v_and_b32_e32 v119, 0xffff0000, v134
	v_lshlrev_b32_e32 v118, 16, v134
	v_pk_mul_f32 v[108:109], v[108:109], v[118:119]
	v_and_b32_e32 v119, 0xffff0000, v103
	v_cvt_pk_bf16_f32 v98, v108, v109
	v_pk_mul_f32 v[108:109], v[144:145], v[30:31] op_sel_hi:[0,1]
	v_pk_fma_f32 v[108:109], v[110:111], v[108:109], 0 op_sel_hi:[1,1,0]
	v_pk_mul_f32 v[110:111], v[32:33], v[40:41] op_sel_hi:[0,1]
	v_lshlrev_b32_e32 v118, 16, v103
	v_and_b32_e32 v103, 0xffff0000, v99
	v_pk_fma_f32 v[108:109], v[114:115], v[110:111], v[108:109]
	v_pk_mul_f32 v[110:111], v[106:107], v[48:49] op_sel_hi:[0,1]
	v_pk_mul_f32 v[102:103], v[118:119], v[102:103]
	v_and_b32_e32 v119, 0xffff0000, v104
	v_pk_fma_f32 v[108:109], v[102:103], v[110:111], v[108:109]
	v_and_b32_e32 v111, 0xffff0000, v135
	v_lshlrev_b32_e32 v110, 16, v135
	v_pk_mul_f32 v[108:109], v[108:109], v[110:111]
	v_pk_mul_f32 v[110:111], v[32:33], v[20:21] op_sel_hi:[0,1]
	v_cvt_pk_bf16_f32 v99, v108, v109
	v_pk_mul_f32 v[108:109], v[144:145], v[16:17] op_sel_hi:[0,1]
	v_pk_fma_f32 v[108:109], v[130:131], v[108:109], 0 op_sel_hi:[1,1,0]
	v_lshlrev_b32_e32 v118, 16, v104
	v_and_b32_e32 v123, 0xffff0000, v100
	v_lshlrev_b32_e32 v122, 16, v100
	v_pk_fma_f32 v[108:109], v[138:139], v[110:111], v[108:109]
	v_pk_mul_f32 v[110:111], v[106:107], v[24:25] op_sel_hi:[0,1]
	v_pk_mul_f32 v[118:119], v[118:119], v[122:123]
	v_lshlrev_b32_e32 v104, 16, v101
	v_pk_fma_f32 v[108:109], v[118:119], v[110:111], v[108:109]
	v_and_b32_e32 v111, 0xffff0000, v136
	v_lshlrev_b32_e32 v110, 16, v136
	v_pk_mul_f32 v[108:109], v[108:109], v[110:111]
	v_pk_mul_f32 v[110:111], v[32:33], v[22:23] op_sel_hi:[0,1]
	v_cvt_pk_bf16_f32 v100, v108, v109
	v_pk_mul_f32 v[108:109], v[144:145], v[18:19] op_sel_hi:[0,1]
	v_pk_fma_f32 v[108:109], v[112:113], v[108:109], 0 op_sel_hi:[1,1,0]
	v_and_b32_e32 v113, 0xffff0000, v105
	v_lshlrev_b32_e32 v112, 16, v105
	v_and_b32_e32 v105, 0xffff0000, v101
	v_pk_fma_f32 v[108:109], v[116:117], v[110:111], v[108:109]
	v_pk_mul_f32 v[110:111], v[106:107], v[26:27] op_sel_hi:[0,1]
	v_pk_mul_f32 v[104:105], v[112:113], v[104:105]
	s_cmpk_lt_i32 s41, 0x801
	v_pk_fma_f32 v[108:109], v[104:105], v[110:111], v[108:109]
	v_and_b32_e32 v111, 0xffff0000, v137
	v_lshlrev_b32_e32 v110, 16, v137
	v_pk_mul_f32 v[108:109], v[108:109], v[110:111]
	v_and_b32_e32 v111, 0xffff0000, v90
	v_cvt_pk_bf16_f32 v101, v108, v109
	v_lshl_add_u64 v[108:109], v[34:35], 0, s[52:53]
	s_cselect_b64 s[52:53], -1, 0
	global_store_dwordx4 v[108:109], v[98:101], off
	s_and_b64 s[52:53], s[46:47], s[52:53]
	v_pk_mul_f32 v[108:109], v[106:107], v[38:39] op_sel_hi:[0,1]
	v_pk_mul_f32 v[100:101], v[32:33], v[28:29] op_sel_hi:[0,1]
	v_cndmask_b32_e64 v98, 0, 1.0, s[52:53]
	v_pk_fma_f32 v[100:101], v[152:153], v[100:101], 0 op_sel_hi:[1,1,0]
	v_lshlrev_b32_e32 v110, 16, v90
	v_and_b32_e32 v113, 0xffff0000, v82
	v_lshlrev_b32_e32 v112, 16, v82
	v_pk_fma_f32 v[100:101], v[120:121], v[108:109], v[100:101]
	v_pk_mul_f32 v[108:109], v[98:99], v[46:47] op_sel_hi:[0,1]
	v_pk_mul_f32 v[110:111], v[110:111], v[112:113]
	v_and_b32_e32 v113, 0xffff0000, v91
	v_pk_fma_f32 v[100:101], v[110:111], v[108:109], v[100:101]
	s_waitcnt vmcnt(7)
	v_and_b32_e32 v109, 0xffff0000, v126
	v_lshlrev_b32_e32 v108, 16, v126
	v_pk_mul_f32 v[100:101], v[100:101], v[108:109]
	v_pk_mul_f32 v[108:109], v[106:107], v[40:41] op_sel_hi:[0,1]
	v_cvt_pk_bf16_f32 v82, v100, v101
	v_pk_mul_f32 v[100:101], v[32:33], v[30:31] op_sel_hi:[0,1]
	v_pk_fma_f32 v[100:101], v[114:115], v[100:101], 0 op_sel_hi:[1,1,0]
	v_lshlrev_b32_e32 v112, 16, v91
	v_and_b32_e32 v91, 0xffff0000, v83
	v_lshlrev_b32_e32 v90, 16, v83
	v_pk_fma_f32 v[100:101], v[102:103], v[108:109], v[100:101]
	v_pk_mul_f32 v[108:109], v[98:99], v[48:49] op_sel_hi:[0,1]
	v_pk_mul_f32 v[90:91], v[112:113], v[90:91]
	v_and_b32_e32 v113, 0xffff0000, v92
	v_pk_fma_f32 v[100:101], v[90:91], v[108:109], v[100:101]
	v_and_b32_e32 v109, 0xffff0000, v127
	v_lshlrev_b32_e32 v108, 16, v127
	v_pk_mul_f32 v[100:101], v[100:101], v[108:109]
	v_pk_mul_f32 v[108:109], v[106:107], v[20:21] op_sel_hi:[0,1]
	v_cvt_pk_bf16_f32 v83, v100, v101
	v_pk_mul_f32 v[100:101], v[32:33], v[16:17] op_sel_hi:[0,1]
	v_pk_fma_f32 v[100:101], v[138:139], v[100:101], 0 op_sel_hi:[1,1,0]
	v_lshlrev_b32_e32 v112, 16, v92
	v_and_b32_e32 v115, 0xffff0000, v84
	v_lshlrev_b32_e32 v114, 16, v84
	v_pk_fma_f32 v[100:101], v[118:119], v[108:109], v[100:101]
	v_pk_mul_f32 v[108:109], v[98:99], v[24:25] op_sel_hi:[0,1]
	v_pk_mul_f32 v[112:113], v[112:113], v[114:115]
	v_and_b32_e32 v115, 0xffff0000, v93
	v_pk_fma_f32 v[100:101], v[112:113], v[108:109], v[100:101]
	v_and_b32_e32 v109, 0xffff0000, v128
	v_lshlrev_b32_e32 v108, 16, v128
	v_pk_mul_f32 v[100:101], v[100:101], v[108:109]
	v_pk_mul_f32 v[108:109], v[106:107], v[22:23] op_sel_hi:[0,1]
	v_cvt_pk_bf16_f32 v84, v100, v101
	v_pk_mul_f32 v[100:101], v[32:33], v[18:19] op_sel_hi:[0,1]
	v_pk_fma_f32 v[100:101], v[116:117], v[100:101], 0 op_sel_hi:[1,1,0]
	v_lshlrev_b32_e32 v114, 16, v93
	v_and_b32_e32 v93, 0xffff0000, v85
	v_lshlrev_b32_e32 v92, 16, v85
	v_pk_fma_f32 v[100:101], v[104:105], v[108:109], v[100:101]
	v_pk_mul_f32 v[108:109], v[98:99], v[26:27] op_sel_hi:[0,1]
	v_pk_mul_f32 v[92:93], v[114:115], v[92:93]
	s_cmpk_lt_i32 s40, 0x801
	v_pk_fma_f32 v[100:101], v[92:93], v[108:109], v[100:101]
	v_and_b32_e32 v109, 0xffff0000, v129
	v_lshlrev_b32_e32 v108, 16, v129
	v_pk_mul_f32 v[100:101], v[100:101], v[108:109]
	s_cselect_b64 s[40:41], -1, 0
	v_cvt_pk_bf16_f32 v85, v100, v101
	v_lshl_add_u64 v[100:101], v[34:35], 0, s[50:51]
	global_store_dwordx4 v[100:101], v[82:85], off
	s_and_b64 s[40:41], s[46:47], s[40:41]
	v_cndmask_b32_e64 v32, 0, 1.0, s[40:41]
	v_pk_mul_f32 v[82:83], v[106:107], v[28:29] op_sel_hi:[0,1]
	v_pk_fma_f32 v[82:83], v[120:121], v[82:83], 0 op_sel_hi:[1,1,0]
	v_pk_mul_f32 v[84:85], v[98:99], v[38:39] op_sel_hi:[0,1]
	v_and_b32_e32 v101, 0xffff0000, v78
	v_lshlrev_b32_e32 v100, 16, v78
	v_and_b32_e32 v109, 0xffff0000, v74
	v_lshlrev_b32_e32 v108, 16, v74
	v_pk_fma_f32 v[82:83], v[110:111], v[84:85], v[82:83]
	v_pk_mul_f32 v[84:85], v[32:33], v[46:47] op_sel_hi:[0,1]
	v_pk_mul_f32 v[100:101], v[100:101], v[108:109]
	v_lshlrev_b32_e32 v78, 16, v75
	v_pk_fma_f32 v[82:83], v[100:101], v[84:85], v[82:83]
	s_waitcnt vmcnt(7)
	v_and_b32_e32 v85, 0xffff0000, v94
	v_lshlrev_b32_e32 v84, 16, v94
	v_pk_mul_f32 v[82:83], v[82:83], v[84:85]
	v_pk_mul_f32 v[84:85], v[98:99], v[40:41] op_sel_hi:[0,1]
	v_cvt_pk_bf16_f32 v74, v82, v83
	v_pk_mul_f32 v[82:83], v[106:107], v[30:31] op_sel_hi:[0,1]
	v_pk_fma_f32 v[82:83], v[102:103], v[82:83], 0 op_sel_hi:[1,1,0]
	v_and_b32_e32 v103, 0xffff0000, v79
	v_lshlrev_b32_e32 v102, 16, v79
	v_and_b32_e32 v79, 0xffff0000, v75
	v_pk_fma_f32 v[82:83], v[90:91], v[84:85], v[82:83]
	v_pk_mul_f32 v[84:85], v[32:33], v[48:49] op_sel_hi:[0,1]
	v_pk_mul_f32 v[78:79], v[102:103], v[78:79]
	v_lshlrev_b32_e32 v94, 16, v80
	v_pk_fma_f32 v[82:83], v[78:79], v[84:85], v[82:83]
	v_and_b32_e32 v85, 0xffff0000, v95
	v_lshlrev_b32_e32 v84, 16, v95
	v_pk_mul_f32 v[82:83], v[82:83], v[84:85]
	v_pk_mul_f32 v[84:85], v[98:99], v[20:21] op_sel_hi:[0,1]
	v_cvt_pk_bf16_f32 v75, v82, v83
	v_pk_mul_f32 v[82:83], v[106:107], v[16:17] op_sel_hi:[0,1]
	v_pk_fma_f32 v[82:83], v[118:119], v[82:83], 0 op_sel_hi:[1,1,0]
	v_and_b32_e32 v95, 0xffff0000, v80
	v_and_b32_e32 v103, 0xffff0000, v76
	v_lshlrev_b32_e32 v102, 16, v76
	v_pk_fma_f32 v[82:83], v[112:113], v[84:85], v[82:83]
	v_pk_mul_f32 v[84:85], v[32:33], v[24:25] op_sel_hi:[0,1]
	v_pk_mul_f32 v[94:95], v[94:95], v[102:103]
	v_and_b32_e32 v103, 0xffff0000, v81
	v_pk_fma_f32 v[82:83], v[94:95], v[84:85], v[82:83]
	v_and_b32_e32 v85, 0xffff0000, v96
	v_lshlrev_b32_e32 v84, 16, v96
	v_pk_mul_f32 v[82:83], v[82:83], v[84:85]
	v_pk_mul_f32 v[84:85], v[98:99], v[22:23] op_sel_hi:[0,1]
	v_cvt_pk_bf16_f32 v76, v82, v83
	v_pk_mul_f32 v[82:83], v[106:107], v[18:19] op_sel_hi:[0,1]
	v_pk_fma_f32 v[82:83], v[104:105], v[82:83], 0 op_sel_hi:[1,1,0]
	v_lshlrev_b32_e32 v102, 16, v81
	v_and_b32_e32 v81, 0xffff0000, v77
	v_lshlrev_b32_e32 v80, 16, v77
	v_pk_fma_f32 v[82:83], v[92:93], v[84:85], v[82:83]
	v_pk_mul_f32 v[84:85], v[32:33], v[26:27] op_sel_hi:[0,1]
	v_pk_mul_f32 v[80:81], v[102:103], v[80:81]
	s_cmpk_lt_i32 s31, 0x801
	v_pk_fma_f32 v[82:83], v[80:81], v[84:85], v[82:83]
	v_and_b32_e32 v85, 0xffff0000, v97
	v_lshlrev_b32_e32 v84, 16, v97
	v_pk_mul_f32 v[82:83], v[82:83], v[84:85]
	s_cselect_b64 s[40:41], -1, 0
	v_cvt_pk_bf16_f32 v77, v82, v83
	v_lshl_add_u64 v[82:83], v[34:35], 0, s[48:49]
	global_store_dwordx4 v[82:83], v[74:77], off
	s_and_b64 s[40:41], s[46:47], s[40:41]
	v_pk_mul_f32 v[82:83], v[32:33], v[38:39] op_sel_hi:[0,1]
	v_pk_mul_f32 v[76:77], v[98:99], v[28:29] op_sel_hi:[0,1]
	v_cndmask_b32_e64 v74, 0, 1.0, s[40:41]
	v_pk_fma_f32 v[76:77], v[110:111], v[76:77], 0 op_sel_hi:[1,1,0]
	v_and_b32_e32 v85, 0xffff0000, v66
	v_lshlrev_b32_e32 v84, 16, v66
	v_and_b32_e32 v97, 0xffff0000, v62
	v_lshlrev_b32_e32 v96, 16, v62
	v_pk_fma_f32 v[76:77], v[100:101], v[82:83], v[76:77]
	v_pk_mul_f32 v[82:83], v[74:75], v[46:47] op_sel_hi:[0,1]
	v_pk_mul_f32 v[84:85], v[84:85], v[96:97]
	v_lshlrev_b32_e32 v66, 16, v63
	v_pk_fma_f32 v[76:77], v[84:85], v[82:83], v[76:77]
	s_waitcnt vmcnt(7)
	v_and_b32_e32 v83, 0xffff0000, v86
	v_lshlrev_b32_e32 v82, 16, v86
	v_pk_mul_f32 v[76:77], v[76:77], v[82:83]
	v_pk_mul_f32 v[82:83], v[32:33], v[40:41] op_sel_hi:[0,1]
	v_cvt_pk_bf16_f32 v62, v76, v77
	v_pk_mul_f32 v[76:77], v[98:99], v[30:31] op_sel_hi:[0,1]
	v_pk_fma_f32 v[76:77], v[90:91], v[76:77], 0 op_sel_hi:[1,1,0]
	v_and_b32_e32 v91, 0xffff0000, v67
	v_lshlrev_b32_e32 v90, 16, v67
	v_and_b32_e32 v67, 0xffff0000, v63
	v_pk_fma_f32 v[76:77], v[78:79], v[82:83], v[76:77]
	v_pk_mul_f32 v[82:83], v[74:75], v[48:49] op_sel_hi:[0,1]
	v_pk_mul_f32 v[66:67], v[90:91], v[66:67]
	v_lshlrev_b32_e32 v86, 16, v68
	v_pk_fma_f32 v[76:77], v[66:67], v[82:83], v[76:77]
	v_and_b32_e32 v83, 0xffff0000, v87
	v_lshlrev_b32_e32 v82, 16, v87
	v_pk_mul_f32 v[76:77], v[76:77], v[82:83]
	v_pk_mul_f32 v[82:83], v[32:33], v[20:21] op_sel_hi:[0,1]
	v_cvt_pk_bf16_f32 v63, v76, v77
	v_pk_mul_f32 v[76:77], v[98:99], v[16:17] op_sel_hi:[0,1]
	v_pk_fma_f32 v[76:77], v[112:113], v[76:77], 0 op_sel_hi:[1,1,0]
	v_and_b32_e32 v87, 0xffff0000, v68
	v_and_b32_e32 v91, 0xffff0000, v64
	v_lshlrev_b32_e32 v90, 16, v64
	v_pk_fma_f32 v[76:77], v[94:95], v[82:83], v[76:77]
	v_pk_mul_f32 v[82:83], v[74:75], v[24:25] op_sel_hi:[0,1]
	v_pk_mul_f32 v[86:87], v[86:87], v[90:91]
	v_and_b32_e32 v91, 0xffff0000, v69
	v_pk_fma_f32 v[76:77], v[86:87], v[82:83], v[76:77]
	v_and_b32_e32 v83, 0xffff0000, v88
	v_lshlrev_b32_e32 v82, 16, v88
	v_pk_mul_f32 v[76:77], v[76:77], v[82:83]
	v_pk_mul_f32 v[82:83], v[32:33], v[22:23] op_sel_hi:[0,1]
	v_cvt_pk_bf16_f32 v64, v76, v77
	v_pk_mul_f32 v[76:77], v[98:99], v[18:19] op_sel_hi:[0,1]
	v_pk_fma_f32 v[76:77], v[92:93], v[76:77], 0 op_sel_hi:[1,1,0]
	v_lshlrev_b32_e32 v90, 16, v69
	v_and_b32_e32 v69, 0xffff0000, v65
	v_lshlrev_b32_e32 v68, 16, v65
	v_pk_fma_f32 v[76:77], v[80:81], v[82:83], v[76:77]
	v_pk_mul_f32 v[82:83], v[74:75], v[26:27] op_sel_hi:[0,1]
	v_pk_mul_f32 v[68:69], v[90:91], v[68:69]
	s_cmpk_lt_i32 s30, 0x801
	v_pk_fma_f32 v[76:77], v[68:69], v[82:83], v[76:77]
	v_and_b32_e32 v83, 0xffff0000, v89
	v_lshlrev_b32_e32 v82, 16, v89
	v_pk_mul_f32 v[76:77], v[76:77], v[82:83]
	s_cselect_b64 s[30:31], -1, 0
	v_cvt_pk_bf16_f32 v65, v76, v77
	v_lshl_add_u64 v[76:77], v[34:35], 0, s[44:45]
	global_store_dwordx4 v[76:77], v[62:65], off
	s_and_b64 s[30:31], s[46:47], s[30:31]
	v_pk_mul_f32 v[76:77], v[74:75], v[38:39] op_sel_hi:[0,1]
	v_pk_mul_f32 v[64:65], v[32:33], v[28:29] op_sel_hi:[0,1]
	v_cndmask_b32_e64 v62, 0, 1.0, s[30:31]
	v_pk_fma_f32 v[64:65], v[100:101], v[64:65], 0 op_sel_hi:[1,1,0]
	v_and_b32_e32 v83, 0xffff0000, v54
	v_lshlrev_b32_e32 v82, 16, v54
	v_and_b32_e32 v89, 0xffff0000, v50
	v_lshlrev_b32_e32 v88, 16, v50
	v_pk_fma_f32 v[64:65], v[84:85], v[76:77], v[64:65]
	v_pk_mul_f32 v[76:77], v[62:63], v[46:47] op_sel_hi:[0,1]
	v_pk_mul_f32 v[82:83], v[82:83], v[88:89]
	v_lshlrev_b32_e32 v54, 16, v51
	v_pk_fma_f32 v[64:65], v[82:83], v[76:77], v[64:65]
	s_waitcnt vmcnt(7)
	v_and_b32_e32 v77, 0xffff0000, v70
	v_lshlrev_b32_e32 v76, 16, v70
	v_pk_mul_f32 v[64:65], v[64:65], v[76:77]
	v_pk_mul_f32 v[76:77], v[74:75], v[40:41] op_sel_hi:[0,1]
	v_cvt_pk_bf16_f32 v50, v64, v65
	v_pk_mul_f32 v[64:65], v[32:33], v[30:31] op_sel_hi:[0,1]
	v_pk_fma_f32 v[64:65], v[78:79], v[64:65], 0 op_sel_hi:[1,1,0]
	v_and_b32_e32 v79, 0xffff0000, v55
	v_lshlrev_b32_e32 v78, 16, v55
	v_and_b32_e32 v55, 0xffff0000, v51
	v_pk_fma_f32 v[64:65], v[66:67], v[76:77], v[64:65]
	v_pk_mul_f32 v[76:77], v[62:63], v[48:49] op_sel_hi:[0,1]
	v_pk_mul_f32 v[54:55], v[78:79], v[54:55]
	v_and_b32_e32 v79, 0xffff0000, v52
	v_pk_fma_f32 v[64:65], v[54:55], v[76:77], v[64:65]
	v_and_b32_e32 v77, 0xffff0000, v71
	v_lshlrev_b32_e32 v76, 16, v71
	v_pk_mul_f32 v[64:65], v[64:65], v[76:77]
	v_pk_mul_f32 v[70:71], v[74:75], v[20:21] op_sel_hi:[0,1]
	v_cvt_pk_bf16_f32 v51, v64, v65
	v_pk_mul_f32 v[64:65], v[32:33], v[16:17] op_sel_hi:[0,1]
	v_pk_fma_f32 v[64:65], v[94:95], v[64:65], 0 op_sel_hi:[1,1,0]
	v_and_b32_e32 v77, 0xffff0000, v56
	v_lshlrev_b32_e32 v76, 16, v56
	v_lshlrev_b32_e32 v78, 16, v52
	v_pk_fma_f32 v[64:65], v[86:87], v[70:71], v[64:65]
	v_pk_mul_f32 v[70:71], v[62:63], v[24:25] op_sel_hi:[0,1]
	v_pk_mul_f32 v[76:77], v[76:77], v[78:79]
	v_and_b32_e32 v79, 0xffff0000, v57
	v_pk_fma_f32 v[64:65], v[76:77], v[70:71], v[64:65]
	v_and_b32_e32 v71, 0xffff0000, v72
	v_lshlrev_b32_e32 v70, 16, v72
	v_pk_mul_f32 v[64:65], v[64:65], v[70:71]
	v_pk_mul_f32 v[70:71], v[74:75], v[22:23] op_sel_hi:[0,1]
	v_cvt_pk_bf16_f32 v52, v64, v65
	v_pk_mul_f32 v[64:65], v[32:33], v[18:19] op_sel_hi:[0,1]
	v_pk_fma_f32 v[64:65], v[80:81], v[64:65], 0 op_sel_hi:[1,1,0]
	v_lshlrev_b32_e32 v78, 16, v57
	v_and_b32_e32 v57, 0xffff0000, v53
	v_lshlrev_b32_e32 v56, 16, v53
	v_pk_fma_f32 v[64:65], v[68:69], v[70:71], v[64:65]
	v_pk_mul_f32 v[70:71], v[62:63], v[26:27] op_sel_hi:[0,1]
	v_pk_mul_f32 v[56:57], v[78:79], v[56:57]
	s_cmpk_lt_u32 s0, 0x100
	v_pk_fma_f32 v[64:65], v[56:57], v[70:71], v[64:65]
	v_and_b32_e32 v71, 0xffff0000, v73
	v_lshlrev_b32_e32 v70, 16, v73
	v_pk_mul_f32 v[64:65], v[64:65], v[70:71]
	s_cselect_b64 s[30:31], -1, 0
	v_cvt_pk_bf16_f32 v53, v64, v65
	v_lshl_add_u64 v[64:65], v[34:35], 0, s[42:43]
	global_store_dwordx4 v[64:65], v[50:53], off
	v_cndmask_b32_e64 v32, 0, 1.0, s[30:31]
	v_and_b32_e32 v65, 0xffff0000, v4
	v_pk_mul_f32 v[50:51], v[74:75], v[28:29] op_sel_hi:[0,1]
	v_pk_fma_f32 v[50:51], v[84:85], v[50:51], 0 op_sel_hi:[1,1,0]
	v_pk_mul_f32 v[52:53], v[62:63], v[38:39] op_sel_hi:[0,1]
	v_lshlrev_b32_e32 v64, 16, v4
	v_and_b32_e32 v71, 0xffff0000, v0
	v_lshlrev_b32_e32 v70, 16, v0
	v_pk_fma_f32 v[50:51], v[82:83], v[52:53], v[50:51]
	v_pk_mul_f32 v[52:53], v[32:33], v[46:47] op_sel_hi:[0,1]
	v_pk_mul_f32 v[64:65], v[64:65], v[70:71]
	v_lshlrev_b32_e32 v4, 16, v1
	v_pk_fma_f32 v[50:51], v[64:65], v[52:53], v[50:51]
	s_waitcnt vmcnt(7)
	v_and_b32_e32 v53, 0xffff0000, v58
	v_lshlrev_b32_e32 v52, 16, v58
	v_pk_mul_f32 v[50:51], v[50:51], v[52:53]
	v_pk_mul_f32 v[52:53], v[62:63], v[40:41] op_sel_hi:[0,1]
	v_cvt_pk_bf16_f32 v0, v50, v51
	v_pk_mul_f32 v[50:51], v[74:75], v[30:31] op_sel_hi:[0,1]
	v_pk_fma_f32 v[50:51], v[66:67], v[50:51], 0 op_sel_hi:[1,1,0]
	v_and_b32_e32 v67, 0xffff0000, v5
	v_lshlrev_b32_e32 v66, 16, v5
	v_and_b32_e32 v5, 0xffff0000, v1
	v_pk_fma_f32 v[50:51], v[54:55], v[52:53], v[50:51]
	v_pk_mul_f32 v[52:53], v[32:33], v[48:49] op_sel_hi:[0,1]
	v_pk_mul_f32 v[4:5], v[66:67], v[4:5]
	v_lshlrev_b32_e32 v58, 16, v6
	v_pk_fma_f32 v[50:51], v[4:5], v[52:53], v[50:51]
	v_and_b32_e32 v53, 0xffff0000, v59
	v_lshlrev_b32_e32 v52, 16, v59
	v_pk_mul_f32 v[50:51], v[50:51], v[52:53]
	v_pk_mul_f32 v[52:53], v[62:63], v[20:21] op_sel_hi:[0,1]
	v_cvt_pk_bf16_f32 v1, v50, v51
	v_pk_mul_f32 v[50:51], v[74:75], v[16:17] op_sel_hi:[0,1]
	v_pk_fma_f32 v[50:51], v[86:87], v[50:51], 0 op_sel_hi:[1,1,0]
	v_and_b32_e32 v59, 0xffff0000, v6
	v_and_b32_e32 v67, 0xffff0000, v2
	v_lshlrev_b32_e32 v66, 16, v2
	v_pk_fma_f32 v[50:51], v[76:77], v[52:53], v[50:51]
	v_pk_mul_f32 v[52:53], v[32:33], v[24:25] op_sel_hi:[0,1]
	v_pk_mul_f32 v[58:59], v[58:59], v[66:67]
	v_and_b32_e32 v67, 0xffff0000, v7
	v_pk_fma_f32 v[50:51], v[58:59], v[52:53], v[50:51]
	v_and_b32_e32 v53, 0xffff0000, v60
	v_lshlrev_b32_e32 v52, 16, v60
	v_pk_mul_f32 v[50:51], v[50:51], v[52:53]
	v_pk_mul_f32 v[52:53], v[62:63], v[22:23] op_sel_hi:[0,1]
	v_cvt_pk_bf16_f32 v2, v50, v51
	v_pk_mul_f32 v[50:51], v[74:75], v[18:19] op_sel_hi:[0,1]
	v_pk_fma_f32 v[50:51], v[68:69], v[50:51], 0 op_sel_hi:[1,1,0]
	v_lshlrev_b32_e32 v66, 16, v7
	v_and_b32_e32 v7, 0xffff0000, v3
	v_lshlrev_b32_e32 v6, 16, v3
	v_pk_fma_f32 v[50:51], v[56:57], v[52:53], v[50:51]
	v_pk_mul_f32 v[52:53], v[32:33], v[26:27] op_sel_hi:[0,1]
	v_pk_mul_f32 v[6:7], v[66:67], v[6:7]
	s_add_i32 s0, s0, 1
	v_pk_fma_f32 v[50:51], v[6:7], v[52:53], v[50:51]
	v_and_b32_e32 v53, 0xffff0000, v61
	v_lshlrev_b32_e32 v52, 16, v61
	v_pk_mul_f32 v[50:51], v[50:51], v[52:53]
	s_cmpk_lt_u32 s0, 0x100
	v_cvt_pk_bf16_f32 v3, v50, v51
	v_lshl_add_u64 v[50:51], v[34:35], 0, s[34:35]
	global_store_dwordx4 v[50:51], v[0:3], off
	s_cselect_b64 s[30:31], -1, 0
	v_cndmask_b32_e64 v50, 0, 1.0, s[30:31]
	v_pk_mul_f32 v[0:1], v[62:63], v[28:29] op_sel_hi:[0,1]
	v_pk_fma_f32 v[0:1], v[82:83], v[0:1], 0 op_sel_hi:[1,1,0]
	v_pk_mul_f32 v[2:3], v[32:33], v[38:39] op_sel_hi:[0,1]
	v_and_b32_e32 v29, 0xffff0000, v12
	v_lshlrev_b32_e32 v28, 16, v12
	v_and_b32_e32 v39, 0xffff0000, v8
	v_lshlrev_b32_e32 v38, 16, v8
	v_pk_fma_f32 v[0:1], v[64:65], v[2:3], v[0:1]
	v_pk_mul_f32 v[2:3], v[50:51], v[46:47] op_sel_hi:[0,1]
	v_pk_mul_f32 v[28:29], v[28:29], v[38:39]
	v_lshlrev_b32_e32 v12, 16, v9
	v_pk_fma_f32 v[0:1], v[28:29], v[2:3], v[0:1]
	s_waitcnt vmcnt(7)
	v_and_b32_e32 v3, 0xffff0000, v42
	v_lshlrev_b32_e32 v2, 16, v42
	v_pk_mul_f32 v[0:1], v[0:1], v[2:3]
	v_pk_mul_f32 v[2:3], v[62:63], v[30:31] op_sel_hi:[0,1]
	v_pk_fma_f32 v[2:3], v[54:55], v[2:3], 0 op_sel_hi:[1,1,0]
	v_pk_mul_f32 v[28:29], v[32:33], v[40:41] op_sel_hi:[0,1]
	v_pk_fma_f32 v[2:3], v[4:5], v[28:29], v[2:3]
	v_and_b32_e32 v29, 0xffff0000, v13
	v_lshlrev_b32_e32 v28, 16, v13
	v_and_b32_e32 v13, 0xffff0000, v9
	v_pk_mul_f32 v[4:5], v[50:51], v[48:49] op_sel_hi:[0,1]
	v_pk_mul_f32 v[8:9], v[28:29], v[12:13]
	v_cvt_pk_bf16_f32 v0, v0, v1
	v_pk_fma_f32 v[2:3], v[8:9], v[4:5], v[2:3]
	v_and_b32_e32 v5, 0xffff0000, v43
	v_lshlrev_b32_e32 v4, 16, v43
	v_pk_mul_f32 v[2:3], v[2:3], v[4:5]
	v_pk_mul_f32 v[4:5], v[32:33], v[20:21] op_sel_hi:[0,1]
	v_cvt_pk_bf16_f32 v1, v2, v3
	v_pk_mul_f32 v[2:3], v[62:63], v[16:17] op_sel_hi:[0,1]
	v_pk_fma_f32 v[2:3], v[76:77], v[2:3], 0 op_sel_hi:[1,1,0]
	v_and_b32_e32 v9, 0xffff0000, v14
	v_lshlrev_b32_e32 v8, 16, v14
	v_and_b32_e32 v13, 0xffff0000, v10
	v_lshlrev_b32_e32 v12, 16, v10
	v_pk_fma_f32 v[2:3], v[58:59], v[4:5], v[2:3]
	v_pk_mul_f32 v[4:5], v[50:51], v[24:25] op_sel_hi:[0,1]
	v_pk_mul_f32 v[8:9], v[8:9], v[12:13]
	v_and_b32_e32 v13, 0xffff0000, v11
	v_pk_fma_f32 v[2:3], v[8:9], v[4:5], v[2:3]
	v_and_b32_e32 v5, 0xffff0000, v44
	v_lshlrev_b32_e32 v4, 16, v44
	v_pk_mul_f32 v[2:3], v[2:3], v[4:5]
	v_pk_mul_f32 v[4:5], v[62:63], v[18:19] op_sel_hi:[0,1]
	v_pk_fma_f32 v[4:5], v[56:57], v[4:5], 0 op_sel_hi:[1,1,0]
	v_pk_mul_f32 v[8:9], v[32:33], v[22:23] op_sel_hi:[0,1]
	v_pk_fma_f32 v[4:5], v[6:7], v[8:9], v[4:5]
	v_and_b32_e32 v9, 0xffff0000, v15
	v_lshlrev_b32_e32 v8, 16, v15
	v_lshlrev_b32_e32 v12, 16, v11
	v_pk_mul_f32 v[6:7], v[50:51], v[26:27] op_sel_hi:[0,1]
	v_pk_mul_f32 v[8:9], v[8:9], v[12:13]
	v_cvt_pk_bf16_f32 v2, v2, v3
	v_pk_fma_f32 v[4:5], v[8:9], v[6:7], v[4:5]
	v_and_b32_e32 v7, 0xffff0000, v45
	v_lshlrev_b32_e32 v6, 16, v45
	v_pk_mul_f32 v[4:5], v[4:5], v[6:7]
	s_nop 0
	v_cvt_pk_bf16_f32 v3, v4, v5
	v_lshl_add_u64 v[4:5], v[34:35], 0, s[26:27]
	global_store_dwordx4 v[4:5], v[0:3], off
